# dpost gate matmul moved from VALU pk_fma loop to v_mfma_f32_16x16x4_f32 (f32 operands, same k-ordered fma chain) with LDS transpose back to thread-per-column layout
# speedup vs baseline: 1.0060x; 1.0060x over previous
.LBB0_634:
	s_or_b64 exec, exec, s[4:5]
	s_waitcnt vmcnt(0)
	v_lshlrev_b32_e32 v4, 16, v9
	v_pk_add_f32 v[6:7], v[6:7], v[4:5] op_sel_hi:[1,0] neg_lo:[0,1] neg_hi:[0,1]
	v_lshl_add_u32 v1, v8, 2, v1
	v_pk_mul_f32 v[2:3], v[2:3], v[6:7]
	s_ashr_i32 s13, s12, 31
	v_add_f32_e32 v2, v2, v4
	v_add_f32_e32 v2, v2, v3
	v_mul_f32_e32 v2, 0xbfb8aa3b, v2
	v_exp_f32_e32 v2, v2
	s_movk_i32 s37, 0x1000
	v_add_f32_e32 v2, 1.0, v2
	v_div_scale_f32 v3, s[4:5], v2, v2, 1.0
	v_rcp_f32_e32 v4, v3
	v_div_scale_f32 v5, vcc, 1.0, v2, 1.0
	s_mul_i32 s4, s12, 0x1a80
	v_fma_f32 v6, -v3, v4, 1.0
	v_fmac_f32_e32 v4, v6, v4
	v_mul_f32_e32 v6, v5, v4
	v_fma_f32 v7, -v3, v6, v5
	v_fmac_f32_e32 v6, v7, v4
	v_fma_f32 v3, -v3, v6, v5
	v_div_fmas_f32 v3, v3, v4, v6
	v_div_fixup_f32 v2, v3, v2, 1.0
	ds_write_b32 v1, v2
	v_ashrrev_i32_e32 v1, 31, v0
	s_mul_hi_i32 s5, s12, 0x1a80
	s_add_u32 s4, s78, s4
	s_addc_u32 s5, s79, s5
	v_lshlrev_b64 v[2:3], 1, v[0:1]
	s_lshl_b64 s[14:15], s[12:13], 8
	v_lshl_add_u64 v[6:7], s[4:5], 0, v[2:3]
	s_or_b32 s4, s12, 1
	v_lshl_add_u64 v[4:5], s[14:15], 0, v[0:1]
	v_add_co_u32_e32 v6, vcc, s37, v6
	s_ashr_i32 s5, s4, 31
	s_mul_i32 s14, s4, 0x1a80
	v_addc_co_u32_e32 v7, vcc, 0, v7, vcc
	v_lshlrev_b64 v[4:5], 1, v[4:5]
	s_mul_hi_i32 s13, s4, 0x1a80
	s_add_u32 s14, s78, s14
	s_waitcnt lgkmcnt(0)
	s_barrier
	global_load_ushort v34, v[6:7], off offset:512 nt
	global_load_ushort v35, v[6:7], off offset:1024 nt
	v_lshl_add_u64 v[6:7], s[80:81], 0, v[4:5]
	v_lshl_add_u64 v[8:9], s[94:95], 0, v[4:5]
	v_lshl_add_u64 v[4:5], s[96:97], 0, v[4:5]
	s_addc_u32 s15, s79, s13
	s_lshl_b64 s[4:5], s[4:5], 8
	global_load_ushort v36, v[6:7], off nt
	global_load_ushort v45, v[8:9], off nt
	global_load_ushort v64, v[4:5], off nt
	v_lshl_add_u64 v[4:5], s[4:5], 0, v[0:1]
	v_lshl_add_u64 v[6:7], s[14:15], 0, v[2:3]
	s_or_b32 s4, s12, 2
	v_add_co_u32_e32 v6, vcc, s37, v6
	s_ashr_i32 s5, s4, 31
	s_mul_i32 s14, s4, 0x1a80
	v_addc_co_u32_e32 v7, vcc, 0, v7, vcc
	v_lshlrev_b64 v[4:5], 1, v[4:5]
	s_mul_hi_i32 s13, s4, 0x1a80
	s_add_u32 s14, s78, s14
	global_load_ushort v65, v[6:7], off offset:512 nt
	global_load_ushort v66, v[6:7], off offset:1024 nt
	v_lshl_add_u64 v[6:7], s[80:81], 0, v[4:5]
	v_lshl_add_u64 v[8:9], s[94:95], 0, v[4:5]
	v_lshl_add_u64 v[4:5], s[96:97], 0, v[4:5]
	s_addc_u32 s15, s79, s13
	s_lshl_b64 s[4:5], s[4:5], 8
	global_load_ushort v67, v[6:7], off nt
	global_load_ushort v68, v[8:9], off nt
	global_load_ushort v69, v[4:5], off nt
	v_lshl_add_u64 v[4:5], s[4:5], 0, v[0:1]
	v_lshl_add_u64 v[6:7], s[14:15], 0, v[2:3]
	s_or_b32 s4, s12, 3
	v_add_co_u32_e32 v6, vcc, s37, v6
	s_ashr_i32 s5, s4, 31
	s_mul_i32 s14, s4, 0x1a80
	v_addc_co_u32_e32 v7, vcc, 0, v7, vcc
	v_lshlrev_b64 v[4:5], 1, v[4:5]
	s_mul_hi_i32 s13, s4, 0x1a80
	s_add_u32 s14, s78, s14
	global_load_ushort v71, v[6:7], off offset:512 nt
	global_load_ushort v72, v[6:7], off offset:1024 nt
	v_lshl_add_u64 v[6:7], s[80:81], 0, v[4:5]
	v_lshl_add_u64 v[8:9], s[94:95], 0, v[4:5]
	v_lshl_add_u64 v[4:5], s[96:97], 0, v[4:5]
	s_addc_u32 s15, s79, s13
	s_lshl_b64 s[4:5], s[4:5], 8
	global_load_ushort v75, v[6:7], off nt
	global_load_ushort v76, v[8:9], off nt
	global_load_ushort v77, v[4:5], off nt
	v_lshl_add_u64 v[4:5], s[4:5], 0, v[0:1]
	v_lshl_add_u64 v[6:7], s[14:15], 0, v[2:3]
	s_or_b32 s4, s12, 4
	v_add_co_u32_e32 v6, vcc, s37, v6
	s_ashr_i32 s5, s4, 31
	s_mul_i32 s14, s4, 0x1a80
	v_addc_co_u32_e32 v7, vcc, 0, v7, vcc
	v_lshlrev_b64 v[4:5], 1, v[4:5]
	s_mul_hi_i32 s13, s4, 0x1a80
	s_add_u32 s14, s78, s14
	global_load_ushort v79, v[6:7], off offset:512 nt
	global_load_ushort v80, v[6:7], off offset:1024 nt
	v_lshl_add_u64 v[6:7], s[80:81], 0, v[4:5]
	v_lshl_add_u64 v[8:9], s[94:95], 0, v[4:5]
	v_lshl_add_u64 v[4:5], s[96:97], 0, v[4:5]
	s_addc_u32 s15, s79, s13
	s_lshl_b64 s[4:5], s[4:5], 8
	global_load_ushort v81, v[6:7], off nt
	global_load_ushort v82, v[8:9], off nt
	global_load_ushort v83, v[4:5], off nt
	v_lshl_add_u64 v[4:5], s[4:5], 0, v[0:1]
	v_lshl_add_u64 v[6:7], s[14:15], 0, v[2:3]
	s_or_b32 s4, s12, 5
	v_add_co_u32_e32 v6, vcc, s37, v6
	s_ashr_i32 s5, s4, 31
	s_mul_i32 s14, s4, 0x1a80
	v_addc_co_u32_e32 v7, vcc, 0, v7, vcc
	v_lshlrev_b64 v[4:5], 1, v[4:5]
	s_mul_hi_i32 s13, s4, 0x1a80
	s_add_u32 s14, s78, s14
	global_load_ushort v85, v[6:7], off offset:512 nt
	global_load_ushort v86, v[6:7], off offset:1024 nt
	v_lshl_add_u64 v[6:7], s[80:81], 0, v[4:5]
	v_lshl_add_u64 v[8:9], s[94:95], 0, v[4:5]
	v_lshl_add_u64 v[4:5], s[96:97], 0, v[4:5]
	s_addc_u32 s15, s79, s13
	s_lshl_b64 s[4:5], s[4:5], 8
	global_load_ushort v87, v[6:7], off nt
	global_load_ushort v88, v[8:9], off nt
	global_load_ushort v84, v[4:5], off nt
	v_lshl_add_u64 v[4:5], s[4:5], 0, v[0:1]
	v_lshl_add_u64 v[6:7], s[14:15], 0, v[2:3]
	s_or_b32 s4, s12, 6
	v_add_co_u32_e32 v6, vcc, s37, v6
	s_ashr_i32 s5, s4, 31
	s_mul_i32 s14, s4, 0x1a80
	v_addc_co_u32_e32 v7, vcc, 0, v7, vcc
	v_lshlrev_b64 v[4:5], 1, v[4:5]
	s_mul_hi_i32 s13, s4, 0x1a80
	s_add_u32 s14, s78, s14
	global_load_ushort v78, v[6:7], off offset:512 nt
	global_load_ushort v89, v[6:7], off offset:1024 nt
	v_lshl_add_u64 v[6:7], s[80:81], 0, v[4:5]
	v_lshl_add_u64 v[8:9], s[94:95], 0, v[4:5]
	v_lshl_add_u64 v[4:5], s[96:97], 0, v[4:5]
	s_addc_u32 s15, s79, s13
	s_lshl_b64 s[4:5], s[4:5], 8
	global_load_ushort v74, v[6:7], off nt
	global_load_ushort v73, v[8:9], off nt
	global_load_ushort v70, v[4:5], off nt
	v_lshl_add_u64 v[4:5], s[4:5], 0, v[0:1]
	v_lshl_add_u64 v[6:7], s[14:15], 0, v[2:3]
	s_or_b32 s4, s12, 7
	v_add_co_u32_e32 v6, vcc, s37, v6
	s_ashr_i32 s5, s4, 31
	s_mul_i32 s14, s4, 0x1a80
	v_addc_co_u32_e32 v7, vcc, 0, v7, vcc
	v_lshlrev_b64 v[4:5], 1, v[4:5]
	s_mul_hi_i32 s13, s4, 0x1a80
	s_add_u32 s14, s78, s14
	global_load_ushort v61, v[6:7], off offset:512 nt
	global_load_ushort v90, v[6:7], off offset:1024 nt
	v_lshl_add_u64 v[6:7], s[80:81], 0, v[4:5]
	v_lshl_add_u64 v[8:9], s[94:95], 0, v[4:5]
	v_lshl_add_u64 v[4:5], s[96:97], 0, v[4:5]
	s_addc_u32 s15, s79, s13
	s_lshl_b64 s[4:5], s[4:5], 8
	global_load_ushort v63, v[6:7], off nt
	global_load_ushort v62, v[8:9], off nt
	global_load_ushort v60, v[4:5], off nt
	v_lshl_add_u64 v[4:5], s[4:5], 0, v[0:1]
	v_lshl_add_u64 v[6:7], s[14:15], 0, v[2:3]
	s_or_b32 s4, s12, 8
	v_add_co_u32_e32 v6, vcc, s37, v6
	s_ashr_i32 s5, s4, 31
	s_mul_i32 s14, s4, 0x1a80
	v_addc_co_u32_e32 v7, vcc, 0, v7, vcc
	v_lshlrev_b64 v[4:5], 1, v[4:5]
	s_mul_hi_i32 s13, s4, 0x1a80
	s_add_u32 s14, s78, s14
	global_load_ushort v59, v[6:7], off offset:512 nt
	global_load_ushort v91, v[6:7], off offset:1024 nt
	v_lshl_add_u64 v[6:7], s[80:81], 0, v[4:5]
	v_lshl_add_u64 v[8:9], s[94:95], 0, v[4:5]
	v_lshl_add_u64 v[4:5], s[96:97], 0, v[4:5]
	s_addc_u32 s15, s79, s13
	s_lshl_b64 s[4:5], s[4:5], 8
	global_load_ushort v58, v[6:7], off nt
	global_load_ushort v57, v[8:9], off nt
	global_load_ushort v56, v[4:5], off nt
	v_lshl_add_u64 v[4:5], s[4:5], 0, v[0:1]
	v_lshl_add_u64 v[6:7], s[14:15], 0, v[2:3]
	s_or_b32 s4, s12, 9
	v_add_co_u32_e32 v6, vcc, s37, v6
	s_ashr_i32 s5, s4, 31
	s_mul_i32 s14, s4, 0x1a80
	v_addc_co_u32_e32 v7, vcc, 0, v7, vcc
	v_lshlrev_b64 v[4:5], 1, v[4:5]
	s_mul_hi_i32 s13, s4, 0x1a80
	s_add_u32 s14, s78, s14
	global_load_ushort v53, v[6:7], off offset:512 nt
	global_load_ushort v92, v[6:7], off offset:1024 nt
	v_lshl_add_u64 v[6:7], s[80:81], 0, v[4:5]
	v_lshl_add_u64 v[8:9], s[94:95], 0, v[4:5]
	v_lshl_add_u64 v[4:5], s[96:97], 0, v[4:5]
	s_addc_u32 s15, s79, s13
	s_lshl_b64 s[4:5], s[4:5], 8
	global_load_ushort v55, v[6:7], off nt
	global_load_ushort v54, v[8:9], off nt
	global_load_ushort v52, v[4:5], off nt
	v_lshl_add_u64 v[4:5], s[4:5], 0, v[0:1]
	v_lshl_add_u64 v[6:7], s[14:15], 0, v[2:3]
	s_or_b32 s4, s12, 10
	v_add_co_u32_e32 v6, vcc, s37, v6
	s_ashr_i32 s5, s4, 31
	s_mul_i32 s14, s4, 0x1a80
	v_addc_co_u32_e32 v7, vcc, 0, v7, vcc
	v_lshlrev_b64 v[4:5], 1, v[4:5]
	s_mul_hi_i32 s13, s4, 0x1a80
	s_add_u32 s14, s78, s14
	global_load_ushort v51, v[6:7], off offset:512 nt
	global_load_ushort v93, v[6:7], off offset:1024 nt
	v_lshl_add_u64 v[6:7], s[80:81], 0, v[4:5]
	v_lshl_add_u64 v[8:9], s[94:95], 0, v[4:5]
	v_lshl_add_u64 v[4:5], s[96:97], 0, v[4:5]
	s_addc_u32 s15, s79, s13
	s_lshl_b64 s[4:5], s[4:5], 8
	global_load_ushort v50, v[6:7], off nt
	global_load_ushort v49, v[8:9], off nt
	global_load_ushort v48, v[4:5], off nt
	v_lshl_add_u64 v[4:5], s[4:5], 0, v[0:1]
	v_lshl_add_u64 v[6:7], s[14:15], 0, v[2:3]
	s_or_b32 s4, s12, 11
	v_add_co_u32_e32 v6, vcc, s37, v6
	s_ashr_i32 s5, s4, 31
	s_mul_i32 s14, s4, 0x1a80
	v_addc_co_u32_e32 v7, vcc, 0, v7, vcc
	v_lshlrev_b64 v[4:5], 1, v[4:5]
	s_mul_hi_i32 s13, s4, 0x1a80
	s_add_u32 s14, s78, s14
	global_load_ushort v44, v[6:7], off offset:512 nt
	global_load_ushort v94, v[6:7], off offset:1024 nt
	v_lshl_add_u64 v[6:7], s[80:81], 0, v[4:5]
	v_lshl_add_u64 v[8:9], s[94:95], 0, v[4:5]
	v_lshl_add_u64 v[4:5], s[96:97], 0, v[4:5]
	s_addc_u32 s15, s79, s13
	s_lshl_b64 s[4:5], s[4:5], 8
	global_load_ushort v47, v[6:7], off nt
	global_load_ushort v46, v[8:9], off nt
	global_load_ushort v43, v[4:5], off nt
	v_lshl_add_u64 v[4:5], s[4:5], 0, v[0:1]
	v_lshl_add_u64 v[6:7], s[14:15], 0, v[2:3]
	s_or_b32 s4, s12, 12
	v_add_co_u32_e32 v6, vcc, s37, v6
	s_ashr_i32 s5, s4, 31
	s_mul_i32 s14, s4, 0x1a80
	v_addc_co_u32_e32 v7, vcc, 0, v7, vcc
	v_lshlrev_b64 v[4:5], 1, v[4:5]
	s_mul_hi_i32 s13, s4, 0x1a80
	s_add_u32 s14, s78, s14
	global_load_ushort v42, v[6:7], off offset:512 nt
	global_load_ushort v95, v[6:7], off offset:1024 nt
	v_lshl_add_u64 v[6:7], s[80:81], 0, v[4:5]
	v_lshl_add_u64 v[8:9], s[94:95], 0, v[4:5]
	v_lshl_add_u64 v[4:5], s[96:97], 0, v[4:5]
	s_addc_u32 s15, s79, s13
	s_lshl_b64 s[4:5], s[4:5], 8
	global_load_ushort v41, v[6:7], off nt
	global_load_ushort v40, v[8:9], off nt
	global_load_ushort v39, v[4:5], off nt
	v_lshl_add_u64 v[4:5], s[4:5], 0, v[0:1]
	v_lshl_add_u64 v[6:7], s[14:15], 0, v[2:3]
	s_or_b32 s4, s12, 13
	v_add_co_u32_e32 v6, vcc, s37, v6
	s_ashr_i32 s5, s4, 31
	s_mul_i32 s14, s4, 0x1a80
	v_addc_co_u32_e32 v7, vcc, 0, v7, vcc
	v_lshlrev_b64 v[4:5], 1, v[4:5]
	s_mul_hi_i32 s13, s4, 0x1a80
	s_add_u32 s14, s78, s14
	global_load_ushort v33, v[6:7], off offset:512 nt
	global_load_ushort v96, v[6:7], off offset:1024 nt
	v_lshl_add_u64 v[6:7], s[80:81], 0, v[4:5]
	v_lshl_add_u64 v[8:9], s[94:95], 0, v[4:5]
	v_lshl_add_u64 v[4:5], s[96:97], 0, v[4:5]
	s_addc_u32 s15, s79, s13
	s_lshl_b64 s[4:5], s[4:5], 8
	global_load_ushort v38, v[6:7], off nt
	global_load_ushort v37, v[8:9], off nt
	global_load_ushort v32, v[4:5], off nt
	v_lshl_add_u64 v[4:5], s[4:5], 0, v[0:1]
	v_lshl_add_u64 v[6:7], s[14:15], 0, v[2:3]
	s_or_b32 s4, s12, 14
	v_add_co_u32_e32 v6, vcc, s37, v6
	s_ashr_i32 s5, s4, 31
	s_mul_i32 s14, s4, 0x1a80
	v_addc_co_u32_e32 v7, vcc, 0, v7, vcc
	v_lshlrev_b64 v[4:5], 1, v[4:5]
	s_mul_hi_i32 s13, s4, 0x1a80
	s_add_u32 s14, s78, s14
	global_load_ushort v31, v[6:7], off offset:512 nt
	global_load_ushort v97, v[6:7], off offset:1024 nt
	v_lshl_add_u64 v[6:7], s[80:81], 0, v[4:5]
	v_lshl_add_u64 v[8:9], s[94:95], 0, v[4:5]
	v_lshl_add_u64 v[4:5], s[96:97], 0, v[4:5]
	s_addc_u32 s15, s79, s13
	s_lshl_b64 s[4:5], s[4:5], 8
	global_load_ushort v30, v[6:7], off nt
	global_load_ushort v29, v[8:9], off nt
	global_load_ushort v28, v[4:5], off nt
	v_lshl_add_u64 v[4:5], s[4:5], 0, v[0:1]
	s_or_b32 s4, s12, 15
	v_lshl_add_u64 v[6:7], s[14:15], 0, v[2:3]
	s_ashr_i32 s5, s4, 31
	s_mul_i32 s14, s4, 0x1a80
	s_mul_hi_i32 s13, s4, 0x1a80
	s_add_u32 s14, s78, s14
	v_add_co_u32_e32 v6, vcc, s37, v6
	s_addc_u32 s15, s79, s13
	s_nop 0
	v_addc_co_u32_e32 v7, vcc, 0, v7, vcc
	v_lshlrev_b64 v[4:5], 1, v[4:5]
	v_lshl_add_u64 v[2:3], s[14:15], 0, v[2:3]
	global_load_ushort v25, v[6:7], off offset:512 nt
	global_load_ushort v98, v[6:7], off offset:1024 nt
	v_lshl_add_u64 v[6:7], s[80:81], 0, v[4:5]
	v_lshl_add_u64 v[8:9], s[94:95], 0, v[4:5]
	v_lshl_add_u64 v[4:5], s[96:97], 0, v[4:5]
	s_lshl_b64 s[4:5], s[4:5], 8
	v_add_co_u32_e32 v2, vcc, s37, v2
	global_load_ushort v27, v[6:7], off nt
	global_load_ushort v26, v[8:9], off nt
	global_load_ushort v24, v[4:5], off nt
	v_lshl_add_u64 v[4:5], s[4:5], 0, v[0:1]
	v_addc_co_u32_e32 v3, vcc, 0, v3, vcc
	global_load_ushort v23, v[2:3], off offset:512 nt
	global_load_ushort v99, v[2:3], off offset:1024 nt
	v_lshlrev_b64 v[2:3], 1, v[4:5]
	v_lshl_add_u64 v[4:5], s[80:81], 0, v[2:3]
	v_lshl_add_u64 v[6:7], s[94:95], 0, v[2:3]
	v_lshl_add_u64 v[2:3], s[96:97], 0, v[2:3]
	global_load_ushort v22, v[4:5], off nt
	global_load_ushort v21, v[6:7], off nt
	global_load_ushort v100, v[2:3], off nt
	v_mov_b32_e32 v2, 0
	s_mov_b32 s4, 0
	v_lshl_add_u64 v[14:15], v[0:1], 2, s[10:11]
	v_mov_b32_e32 v3, v2
	v_mov_b32_e32 v18, v2
	v_mov_b32_e32 v19, v2
	v_mov_b32_e32 v16, v2
	v_mov_b32_e32 v17, v2
	v_mov_b32_e32 v12, v2
	v_mov_b32_e32 v13, v2
	v_mov_b32_e32 v10, v2
	v_mov_b32_e32 v11, v2
	v_mov_b32_e32 v8, v2
	v_mov_b32_e32 v9, v2
	v_mov_b32_e32 v6, v2
	v_mov_b32_e32 v7, v2
	v_mov_b32_e32 v4, v2
	v_mov_b32_e32 v5, v2
	v_and_b32_e32 v232, 63, v179
	v_and_b32_e32 v233, 15, v232
	v_lshrrev_b32_e32 v248, 4, v232
	v_lshlrev_b32_e32 v246, 4, v233
	v_lshl_add_u32 v246, v248, 10, v246
	v_lshlrev_b32_e32 v252, 2, v232
	v_sub_u32_e32 v246, v246, v252
	v_add_u32_e32 v246, 0xfffff800, v246
	v_ashrrev_i32_e32 v247, 31, v246
	v_lshl_add_u64 v[246:247], v[14:15], 0, v[246:247]
	v_lshrrev_b32_e32 v249, 6, v179
	v_lshlrev_b32_e32 v249, 12, v249
	v_add_u32_e32 v249, 0x8000, v249
	v_lshl_add_u32 v252, v232, 6, v249
	v_lshl_add_u32 v249, v233, 8, v249
	v_lshl_add_u32 v249, v248, 4, v249
	v_lshl_add_u32 v248, v232, 2, 16
	global_load_dwordx4 v[144:147], v[246:247], off
	v_lshl_add_u64 v[246:247], v[246:247], 0, s[64:65]
	ds_read_b32 v136, v248 offset:0
	global_load_dwordx4 v[148:151], v[246:247], off
	v_lshl_add_u64 v[246:247], v[246:247], 0, s[64:65]
	ds_read_b32 v137, v248 offset:256
	global_load_dwordx4 v[152:155], v[246:247], off
	v_lshl_add_u64 v[246:247], v[246:247], 0, s[64:65]
	ds_read_b32 v138, v248 offset:512
	global_load_dwordx4 v[166:169], v[246:247], off
	v_lshl_add_u64 v[246:247], v[246:247], 0, s[64:65]
	ds_read_b32 v139, v248 offset:768
	global_load_dwordx4 v[170:173], v[246:247], off
	v_lshl_add_u64 v[246:247], v[246:247], 0, s[64:65]
	ds_read_b32 v140, v248 offset:1024
	global_load_dwordx4 v[180:183], v[246:247], off
	v_lshl_add_u64 v[246:247], v[246:247], 0, s[64:65]
	ds_read_b32 v141, v248 offset:1280
	global_load_dwordx4 v[238:241], v[246:247], off
	v_lshl_add_u64 v[246:247], v[246:247], 0, s[64:65]
	ds_read_b32 v142, v248 offset:1536
	global_load_dwordx4 v[242:245], v[246:247], off
	v_lshl_add_u64 v[246:247], v[246:247], 0, s[64:65]
	ds_read_b32 v143, v248 offset:1792
	s_waitcnt vmcnt(7)
	s_waitcnt lgkmcnt(7)
	v_mfma_f32_16x16x4_f32 v[120:123], v136, v144, 0
	v_mfma_f32_16x16x4_f32 v[124:127], v136, v145, 0
	v_mfma_f32_16x16x4_f32 v[128:131], v136, v146, 0
	v_mfma_f32_16x16x4_f32 v[132:135], v136, v147, 0
	s_waitcnt vmcnt(6)
	s_waitcnt lgkmcnt(6)
	v_mfma_f32_16x16x4_f32 v[120:123], v137, v148, v[120:123]
	v_mfma_f32_16x16x4_f32 v[124:127], v137, v149, v[124:127]
	v_mfma_f32_16x16x4_f32 v[128:131], v137, v150, v[128:131]
	v_mfma_f32_16x16x4_f32 v[132:135], v137, v151, v[132:135]
	s_waitcnt vmcnt(5)
	s_waitcnt lgkmcnt(5)
	v_mfma_f32_16x16x4_f32 v[120:123], v138, v152, v[120:123]
	v_mfma_f32_16x16x4_f32 v[124:127], v138, v153, v[124:127]
	v_mfma_f32_16x16x4_f32 v[128:131], v138, v154, v[128:131]
	v_mfma_f32_16x16x4_f32 v[132:135], v138, v155, v[132:135]
	s_waitcnt vmcnt(4)
	s_waitcnt lgkmcnt(4)
	v_mfma_f32_16x16x4_f32 v[120:123], v139, v166, v[120:123]
	v_mfma_f32_16x16x4_f32 v[124:127], v139, v167, v[124:127]
	v_mfma_f32_16x16x4_f32 v[128:131], v139, v168, v[128:131]
	v_mfma_f32_16x16x4_f32 v[132:135], v139, v169, v[132:135]
	global_load_dwordx4 v[144:147], v[246:247], off
	v_lshl_add_u64 v[246:247], v[246:247], 0, s[64:65]
	ds_read_b32 v136, v248 offset:2048
	global_load_dwordx4 v[148:151], v[246:247], off
	v_lshl_add_u64 v[246:247], v[246:247], 0, s[64:65]
	ds_read_b32 v137, v248 offset:2304
	global_load_dwordx4 v[152:155], v[246:247], off
	v_lshl_add_u64 v[246:247], v[246:247], 0, s[64:65]
	ds_read_b32 v138, v248 offset:2560
	global_load_dwordx4 v[166:169], v[246:247], off
	v_lshl_add_u64 v[246:247], v[246:247], 0, s[64:65]
	ds_read_b32 v139, v248 offset:2816
	s_waitcnt vmcnt(7)
	s_waitcnt lgkmcnt(7)
	v_mfma_f32_16x16x4_f32 v[120:123], v140, v170, v[120:123]
	v_mfma_f32_16x16x4_f32 v[124:127], v140, v171, v[124:127]
	v_mfma_f32_16x16x4_f32 v[128:131], v140, v172, v[128:131]
	v_mfma_f32_16x16x4_f32 v[132:135], v140, v173, v[132:135]
	s_waitcnt vmcnt(6)
	s_waitcnt lgkmcnt(6)
	v_mfma_f32_16x16x4_f32 v[120:123], v141, v180, v[120:123]
	v_mfma_f32_16x16x4_f32 v[124:127], v141, v181, v[124:127]
	v_mfma_f32_16x16x4_f32 v[128:131], v141, v182, v[128:131]
	v_mfma_f32_16x16x4_f32 v[132:135], v141, v183, v[132:135]
	s_waitcnt vmcnt(5)
	s_waitcnt lgkmcnt(5)
	v_mfma_f32_16x16x4_f32 v[120:123], v142, v238, v[120:123]
	v_mfma_f32_16x16x4_f32 v[124:127], v142, v239, v[124:127]
	v_mfma_f32_16x16x4_f32 v[128:131], v142, v240, v[128:131]
	v_mfma_f32_16x16x4_f32 v[132:135], v142, v241, v[132:135]
	s_waitcnt vmcnt(4)
	s_waitcnt lgkmcnt(4)
	v_mfma_f32_16x16x4_f32 v[120:123], v143, v242, v[120:123]
	v_mfma_f32_16x16x4_f32 v[124:127], v143, v243, v[124:127]
	v_mfma_f32_16x16x4_f32 v[128:131], v143, v244, v[128:131]
	v_mfma_f32_16x16x4_f32 v[132:135], v143, v245, v[132:135]
	global_load_dwordx4 v[170:173], v[246:247], off
	v_lshl_add_u64 v[246:247], v[246:247], 0, s[64:65]
	ds_read_b32 v140, v248 offset:3072
	global_load_dwordx4 v[180:183], v[246:247], off
	v_lshl_add_u64 v[246:247], v[246:247], 0, s[64:65]
	ds_read_b32 v141, v248 offset:3328
	global_load_dwordx4 v[238:241], v[246:247], off
	v_lshl_add_u64 v[246:247], v[246:247], 0, s[64:65]
	ds_read_b32 v142, v248 offset:3584
	global_load_dwordx4 v[242:245], v[246:247], off
	v_lshl_add_u64 v[246:247], v[246:247], 0, s[64:65]
	ds_read_b32 v143, v248 offset:3840
	s_waitcnt vmcnt(7)
	s_waitcnt lgkmcnt(7)
	v_mfma_f32_16x16x4_f32 v[120:123], v136, v144, v[120:123]
	v_mfma_f32_16x16x4_f32 v[124:127], v136, v145, v[124:127]
	v_mfma_f32_16x16x4_f32 v[128:131], v136, v146, v[128:131]
	v_mfma_f32_16x16x4_f32 v[132:135], v136, v147, v[132:135]
	s_waitcnt vmcnt(6)
	s_waitcnt lgkmcnt(6)
	v_mfma_f32_16x16x4_f32 v[120:123], v137, v148, v[120:123]
	v_mfma_f32_16x16x4_f32 v[124:127], v137, v149, v[124:127]
	v_mfma_f32_16x16x4_f32 v[128:131], v137, v150, v[128:131]
	v_mfma_f32_16x16x4_f32 v[132:135], v137, v151, v[132:135]
	s_waitcnt vmcnt(5)
	s_waitcnt lgkmcnt(5)
	v_mfma_f32_16x16x4_f32 v[120:123], v138, v152, v[120:123]
	v_mfma_f32_16x16x4_f32 v[124:127], v138, v153, v[124:127]
	v_mfma_f32_16x16x4_f32 v[128:131], v138, v154, v[128:131]
	v_mfma_f32_16x16x4_f32 v[132:135], v138, v155, v[132:135]
	s_waitcnt vmcnt(4)
	s_waitcnt lgkmcnt(4)
	v_mfma_f32_16x16x4_f32 v[120:123], v139, v166, v[120:123]
	v_mfma_f32_16x16x4_f32 v[124:127], v139, v167, v[124:127]
	v_mfma_f32_16x16x4_f32 v[128:131], v139, v168, v[128:131]
	v_mfma_f32_16x16x4_f32 v[132:135], v139, v169, v[132:135]
	global_load_dwordx4 v[144:147], v[246:247], off
	v_lshl_add_u64 v[246:247], v[246:247], 0, s[64:65]
	ds_read_b32 v136, v248 offset:4096
	global_load_dwordx4 v[148:151], v[246:247], off
	v_lshl_add_u64 v[246:247], v[246:247], 0, s[64:65]
	ds_read_b32 v137, v248 offset:4352
	global_load_dwordx4 v[152:155], v[246:247], off
	v_lshl_add_u64 v[246:247], v[246:247], 0, s[64:65]
	ds_read_b32 v138, v248 offset:4608
	global_load_dwordx4 v[166:169], v[246:247], off
	v_lshl_add_u64 v[246:247], v[246:247], 0, s[64:65]
	ds_read_b32 v139, v248 offset:4864
	s_waitcnt vmcnt(7)
	s_waitcnt lgkmcnt(7)
	v_mfma_f32_16x16x4_f32 v[120:123], v140, v170, v[120:123]
	v_mfma_f32_16x16x4_f32 v[124:127], v140, v171, v[124:127]
	v_mfma_f32_16x16x4_f32 v[128:131], v140, v172, v[128:131]
	v_mfma_f32_16x16x4_f32 v[132:135], v140, v173, v[132:135]
	s_waitcnt vmcnt(6)
	s_waitcnt lgkmcnt(6)
	v_mfma_f32_16x16x4_f32 v[120:123], v141, v180, v[120:123]
	v_mfma_f32_16x16x4_f32 v[124:127], v141, v181, v[124:127]
	v_mfma_f32_16x16x4_f32 v[128:131], v141, v182, v[128:131]
	v_mfma_f32_16x16x4_f32 v[132:135], v141, v183, v[132:135]
	s_waitcnt vmcnt(5)
	s_waitcnt lgkmcnt(5)
	v_mfma_f32_16x16x4_f32 v[120:123], v142, v238, v[120:123]
	v_mfma_f32_16x16x4_f32 v[124:127], v142, v239, v[124:127]
	v_mfma_f32_16x16x4_f32 v[128:131], v142, v240, v[128:131]
	v_mfma_f32_16x16x4_f32 v[132:135], v142, v241, v[132:135]
	s_waitcnt vmcnt(4)
	s_waitcnt lgkmcnt(4)
	v_mfma_f32_16x16x4_f32 v[120:123], v143, v242, v[120:123]
	v_mfma_f32_16x16x4_f32 v[124:127], v143, v243, v[124:127]
	v_mfma_f32_16x16x4_f32 v[128:131], v143, v244, v[128:131]
	v_mfma_f32_16x16x4_f32 v[132:135], v143, v245, v[132:135]
	global_load_dwordx4 v[170:173], v[246:247], off
	v_lshl_add_u64 v[246:247], v[246:247], 0, s[64:65]
	ds_read_b32 v140, v248 offset:5120
	global_load_dwordx4 v[180:183], v[246:247], off
	v_lshl_add_u64 v[246:247], v[246:247], 0, s[64:65]
	ds_read_b32 v141, v248 offset:5376
	global_load_dwordx4 v[238:241], v[246:247], off
	v_lshl_add_u64 v[246:247], v[246:247], 0, s[64:65]
	ds_read_b32 v142, v248 offset:5632
	global_load_dwordx4 v[242:245], v[246:247], off
	v_lshl_add_u64 v[246:247], v[246:247], 0, s[64:65]
	ds_read_b32 v143, v248 offset:5888
	s_waitcnt vmcnt(7)
	s_waitcnt lgkmcnt(7)
	v_mfma_f32_16x16x4_f32 v[120:123], v136, v144, v[120:123]
	v_mfma_f32_16x16x4_f32 v[124:127], v136, v145, v[124:127]
	v_mfma_f32_16x16x4_f32 v[128:131], v136, v146, v[128:131]
	v_mfma_f32_16x16x4_f32 v[132:135], v136, v147, v[132:135]
	s_waitcnt vmcnt(6)
	s_waitcnt lgkmcnt(6)
	v_mfma_f32_16x16x4_f32 v[120:123], v137, v148, v[120:123]
	v_mfma_f32_16x16x4_f32 v[124:127], v137, v149, v[124:127]
	v_mfma_f32_16x16x4_f32 v[128:131], v137, v150, v[128:131]
	v_mfma_f32_16x16x4_f32 v[132:135], v137, v151, v[132:135]
	s_waitcnt vmcnt(5)
	s_waitcnt lgkmcnt(5)
	v_mfma_f32_16x16x4_f32 v[120:123], v138, v152, v[120:123]
	v_mfma_f32_16x16x4_f32 v[124:127], v138, v153, v[124:127]
	v_mfma_f32_16x16x4_f32 v[128:131], v138, v154, v[128:131]
	v_mfma_f32_16x16x4_f32 v[132:135], v138, v155, v[132:135]
	s_waitcnt vmcnt(4)
	s_waitcnt lgkmcnt(4)
	v_mfma_f32_16x16x4_f32 v[120:123], v139, v166, v[120:123]
	v_mfma_f32_16x16x4_f32 v[124:127], v139, v167, v[124:127]
	v_mfma_f32_16x16x4_f32 v[128:131], v139, v168, v[128:131]
	v_mfma_f32_16x16x4_f32 v[132:135], v139, v169, v[132:135]
	global_load_dwordx4 v[144:147], v[246:247], off
	v_lshl_add_u64 v[246:247], v[246:247], 0, s[64:65]
	ds_read_b32 v136, v248 offset:6144
	global_load_dwordx4 v[148:151], v[246:247], off
	v_lshl_add_u64 v[246:247], v[246:247], 0, s[64:65]
	ds_read_b32 v137, v248 offset:6400
	global_load_dwordx4 v[152:155], v[246:247], off
	v_lshl_add_u64 v[246:247], v[246:247], 0, s[64:65]
	ds_read_b32 v138, v248 offset:6656
	global_load_dwordx4 v[166:169], v[246:247], off
	v_lshl_add_u64 v[246:247], v[246:247], 0, s[64:65]
	ds_read_b32 v139, v248 offset:6912
	s_waitcnt vmcnt(7)
	s_waitcnt lgkmcnt(7)
	v_mfma_f32_16x16x4_f32 v[120:123], v140, v170, v[120:123]
	v_mfma_f32_16x16x4_f32 v[124:127], v140, v171, v[124:127]
	v_mfma_f32_16x16x4_f32 v[128:131], v140, v172, v[128:131]
	v_mfma_f32_16x16x4_f32 v[132:135], v140, v173, v[132:135]
	s_waitcnt vmcnt(6)
	s_waitcnt lgkmcnt(6)
	v_mfma_f32_16x16x4_f32 v[120:123], v141, v180, v[120:123]
	v_mfma_f32_16x16x4_f32 v[124:127], v141, v181, v[124:127]
	v_mfma_f32_16x16x4_f32 v[128:131], v141, v182, v[128:131]
	v_mfma_f32_16x16x4_f32 v[132:135], v141, v183, v[132:135]
	s_waitcnt vmcnt(5)
	s_waitcnt lgkmcnt(5)
	v_mfma_f32_16x16x4_f32 v[120:123], v142, v238, v[120:123]
	v_mfma_f32_16x16x4_f32 v[124:127], v142, v239, v[124:127]
	v_mfma_f32_16x16x4_f32 v[128:131], v142, v240, v[128:131]
	v_mfma_f32_16x16x4_f32 v[132:135], v142, v241, v[132:135]
	s_waitcnt vmcnt(4)
	s_waitcnt lgkmcnt(4)
	v_mfma_f32_16x16x4_f32 v[120:123], v143, v242, v[120:123]
	v_mfma_f32_16x16x4_f32 v[124:127], v143, v243, v[124:127]
	v_mfma_f32_16x16x4_f32 v[128:131], v143, v244, v[128:131]
	v_mfma_f32_16x16x4_f32 v[132:135], v143, v245, v[132:135]
	global_load_dwordx4 v[170:173], v[246:247], off
	v_lshl_add_u64 v[246:247], v[246:247], 0, s[64:65]
	ds_read_b32 v140, v248 offset:7168
	global_load_dwordx4 v[180:183], v[246:247], off
	v_lshl_add_u64 v[246:247], v[246:247], 0, s[64:65]
	ds_read_b32 v141, v248 offset:7424
	global_load_dwordx4 v[238:241], v[246:247], off
	v_lshl_add_u64 v[246:247], v[246:247], 0, s[64:65]
	ds_read_b32 v142, v248 offset:7680
	global_load_dwordx4 v[242:245], v[246:247], off
	v_lshl_add_u64 v[246:247], v[246:247], 0, s[64:65]
	ds_read_b32 v143, v248 offset:7936
	s_waitcnt vmcnt(7)
	s_waitcnt lgkmcnt(7)
	v_mfma_f32_16x16x4_f32 v[120:123], v136, v144, v[120:123]
	v_mfma_f32_16x16x4_f32 v[124:127], v136, v145, v[124:127]
	v_mfma_f32_16x16x4_f32 v[128:131], v136, v146, v[128:131]
	v_mfma_f32_16x16x4_f32 v[132:135], v136, v147, v[132:135]
	s_waitcnt vmcnt(6)
	s_waitcnt lgkmcnt(6)
	v_mfma_f32_16x16x4_f32 v[120:123], v137, v148, v[120:123]
	v_mfma_f32_16x16x4_f32 v[124:127], v137, v149, v[124:127]
	v_mfma_f32_16x16x4_f32 v[128:131], v137, v150, v[128:131]
	v_mfma_f32_16x16x4_f32 v[132:135], v137, v151, v[132:135]
	s_waitcnt vmcnt(5)
	s_waitcnt lgkmcnt(5)
	v_mfma_f32_16x16x4_f32 v[120:123], v138, v152, v[120:123]
	v_mfma_f32_16x16x4_f32 v[124:127], v138, v153, v[124:127]
	v_mfma_f32_16x16x4_f32 v[128:131], v138, v154, v[128:131]
	v_mfma_f32_16x16x4_f32 v[132:135], v138, v155, v[132:135]
	s_waitcnt vmcnt(4)
	s_waitcnt lgkmcnt(4)
	v_mfma_f32_16x16x4_f32 v[120:123], v139, v166, v[120:123]
	v_mfma_f32_16x16x4_f32 v[124:127], v139, v167, v[124:127]
	v_mfma_f32_16x16x4_f32 v[128:131], v139, v168, v[128:131]
	v_mfma_f32_16x16x4_f32 v[132:135], v139, v169, v[132:135]
	s_waitcnt vmcnt(3)
	s_waitcnt lgkmcnt(3)
	v_mfma_f32_16x16x4_f32 v[120:123], v140, v170, v[120:123]
	v_mfma_f32_16x16x4_f32 v[124:127], v140, v171, v[124:127]
	v_mfma_f32_16x16x4_f32 v[128:131], v140, v172, v[128:131]
	v_mfma_f32_16x16x4_f32 v[132:135], v140, v173, v[132:135]
	s_waitcnt vmcnt(2)
	s_waitcnt lgkmcnt(2)
	v_mfma_f32_16x16x4_f32 v[120:123], v141, v180, v[120:123]
	v_mfma_f32_16x16x4_f32 v[124:127], v141, v181, v[124:127]
	v_mfma_f32_16x16x4_f32 v[128:131], v141, v182, v[128:131]
	v_mfma_f32_16x16x4_f32 v[132:135], v141, v183, v[132:135]
	s_waitcnt vmcnt(1)
	s_waitcnt lgkmcnt(1)
	v_mfma_f32_16x16x4_f32 v[120:123], v142, v238, v[120:123]
	v_mfma_f32_16x16x4_f32 v[124:127], v142, v239, v[124:127]
	v_mfma_f32_16x16x4_f32 v[128:131], v142, v240, v[128:131]
	v_mfma_f32_16x16x4_f32 v[132:135], v142, v241, v[132:135]
	s_waitcnt vmcnt(0)
	s_waitcnt lgkmcnt(0)
	v_mfma_f32_16x16x4_f32 v[120:123], v143, v242, v[120:123]
	v_mfma_f32_16x16x4_f32 v[124:127], v143, v243, v[124:127]
	v_mfma_f32_16x16x4_f32 v[128:131], v143, v244, v[128:131]
	v_mfma_f32_16x16x4_f32 v[132:135], v143, v245, v[132:135]
	s_waitcnt vmcnt(0)
	s_nop 15
	ds_write_b128 v249, v[120:123] offset:0
	ds_write_b128 v249, v[124:127] offset:64
	ds_write_b128 v249, v[128:131] offset:128
	ds_write_b128 v249, v[132:135] offset:192
	s_waitcnt lgkmcnt(0)
	ds_read_b64 v[18:19], v252 offset:0
	ds_read_b64 v[16:17], v252 offset:8
	ds_read_b64 v[12:13], v252 offset:16
	ds_read_b64 v[10:11], v252 offset:24
	ds_read_b64 v[8:9], v252 offset:32
	ds_read_b64 v[6:7], v252 offset:40
	ds_read_b64 v[4:5], v252 offset:48
	ds_read_b64 v[2:3], v252 offset:56
	s_waitcnt lgkmcnt(0)
	v_lshlrev_b32_e32 v14, 16, v23
	v_lshlrev_b32_e32 v15, 16, v99
	v_add_f32_e32 v23, v15, v14
	v_lshlrev_b32_e32 v14, 16, v25
	v_lshlrev_b32_e32 v15, 16, v98
	v_add_f32_e32 v25, v15, v14
	v_lshlrev_b32_e32 v14, 16, v31
	v_lshlrev_b32_e32 v15, 16, v97
	v_add_f32_e32 v31, v15, v14
	v_lshlrev_b32_e32 v14, 16, v33
	v_lshlrev_b32_e32 v15, 16, v96
	v_add_f32_e32 v33, v15, v14
	v_lshlrev_b32_e32 v14, 16, v42
	v_lshlrev_b32_e32 v15, 16, v95
	v_add_f32_e32 v42, v15, v14
	v_lshlrev_b32_e32 v14, 16, v44
	v_lshlrev_b32_e32 v15, 16, v94
	v_add_f32_e32 v44, v15, v14
	v_lshlrev_b32_e32 v14, 16, v51
	v_lshlrev_b32_e32 v15, 16, v93
	v_add_f32_e32 v51, v15, v14
	v_lshlrev_b32_e32 v14, 16, v53
	v_lshlrev_b32_e32 v15, 16, v92
	v_add_f32_e32 v53, v15, v14
	v_lshlrev_b32_e32 v14, 16, v59
	v_lshlrev_b32_e32 v15, 16, v91
	v_add_f32_e32 v59, v15, v14
	v_lshlrev_b32_e32 v14, 16, v61
	v_lshlrev_b32_e32 v15, 16, v90
	v_add_f32_e32 v61, v15, v14
	v_lshlrev_b32_e32 v14, 16, v78
	v_lshlrev_b32_e32 v15, 16, v89
	v_add_f32_e32 v78, v15, v14
	v_lshlrev_b32_e32 v14, 16, v85
	v_lshlrev_b32_e32 v15, 16, v86
	v_add_f32_e32 v85, v15, v14
	v_lshlrev_b32_e32 v14, 16, v79
	v_lshlrev_b32_e32 v15, 16, v80
	v_add_f32_e32 v79, v15, v14
	v_lshlrev_b32_e32 v14, 16, v71
	v_lshlrev_b32_e32 v15, 16, v72
	v_add_f32_e32 v71, v15, v14
	v_lshlrev_b32_e32 v14, 16, v65
	v_lshlrev_b32_e32 v15, 16, v66
	v_add_f32_e32 v65, v15, v14
	v_lshlrev_b32_e32 v14, 16, v34
	v_lshlrev_b32_e32 v15, 16, v35
	v_add_f32_e32 v66, v15, v14
	v_add_u32_e32 v14, s24, v0
	v_ashrrev_i32_e32 v15, 31, v14
	v_readlane_b32 s48, v253, 42
	v_lshlrev_b64 v[14:15], 2, v[14:15]
	v_readlane_b32 s60, v253, 54
	v_readlane_b32 s61, v253, 55
	v_readlane_b32 s62, v253, 56
	v_readlane_b32 s63, v253, 57
	v_lshl_add_u64 v[90:91], s[68:69], 0, v[14:15]
	v_lshlrev_b32_e32 v80, 16, v36
	v_lshl_add_u64 v[34:35], s[62:63], 0, v[14:15]
	v_lshl_add_u64 v[14:15], s[60:61], 0, v[14:15]
	global_load_dword v36, v[14:15], off
	v_lshlrev_b32_e32 v72, 16, v45
	global_load_dword v35, v[34:35], off
	v_add_f32_dpp v14, v66, v66 quad_perm:[1,0,3,2] row_mask:0xf bank_mask:0xf bound_ctrl:1
	global_load_dword v34, v[90:91], off
	v_mul_f32_e32 v72, v80, v72
	v_add_f32_dpp v14, v14, v14 quad_perm:[2,3,0,1] row_mask:0xf bank_mask:0xf bound_ctrl:1
	s_mov_b32 s46, 0x3c800000
	v_lshlrev_b32_e32 v64, 16, v64
	v_add_f32_dpp v14, v14, v14 row_half_mirror row_mask:0xf bank_mask:0xf bound_ctrl:1
	v_lshl_add_u32 v45, v0, 1, 16
	v_lshlrev_b32_e32 v68, 16, v68
	v_add_f32_dpp v14, v14, v14 row_mirror row_mask:0xf bank_mask:0xf bound_ctrl:1
	v_lshlrev_b32_e32 v67, 16, v67
	v_readlane_b32 s13, v14, 16
	v_readlane_b32 s14, v14, 48
	v_readlane_b32 s4, v14, 0
	v_readlane_b32 s5, v14, 32
	v_mov_b32_e32 v14, s13
	v_mov_b32_e32 v15, s14
	v_pk_add_f32 v[14:15], s[4:5], v[14:15]
	v_lshlrev_b32_e32 v69, 16, v69
	v_add_f32_e32 v14, v14, v15
	v_fmac_f32_e32 v66, 0xbc800000, v14
	v_mul_f32_e32 v14, v66, v66
	v_lshlrev_b32_e32 v76, 16, v76
	v_lshlrev_b32_e32 v75, 16, v75
	v_mov_b32_dpp v14, v14 quad_perm:[1,0,3,2] row_mask:0xf bank_mask:0xf bound_ctrl:1
	v_fmac_f32_e32 v14, v66, v66
	v_lshlrev_b32_e32 v77, 16, v77
	v_lshlrev_b32_e32 v82, 16, v82
	v_add_f32_dpp v14, v14, v14 quad_perm:[2,3,0,1] row_mask:0xf bank_mask:0xf bound_ctrl:1
	v_lshlrev_b32_e32 v81, 16, v81
	v_lshlrev_b32_e32 v83, 16, v83
	v_add_f32_dpp v14, v14, v14 row_half_mirror row_mask:0xf bank_mask:0xf bound_ctrl:1
	v_lshlrev_b32_e32 v88, 16, v88
	v_lshlrev_b32_e32 v87, 16, v87
	v_add_f32_dpp v14, v14, v14 row_mirror row_mask:0xf bank_mask:0xf bound_ctrl:1
	v_lshlrev_b32_e32 v84, 16, v84
	v_readlane_b32 s13, v14, 16
	v_readlane_b32 s14, v14, 48
	v_readlane_b32 s4, v14, 0
	v_readlane_b32 s5, v14, 32
	v_mov_b32_e32 v14, s13
	v_mov_b32_e32 v15, s14
	v_pk_add_f32 v[14:15], s[4:5], v[14:15]
	v_lshlrev_b32_e32 v73, 16, v73
	v_mov_b32_e32 v93, v14
	v_lshlrev_b32_e32 v74, 16, v74
	v_lshlrev_b32_e32 v70, 16, v70
	v_lshlrev_b32_e32 v62, 16, v62
	v_lshlrev_b32_e32 v63, 16, v63
	v_lshlrev_b32_e32 v60, 16, v60
	v_lshlrev_b32_e32 v57, 16, v57
	v_lshlrev_b32_e32 v58, 16, v58
	v_lshlrev_b32_e32 v56, 16, v56
	v_lshlrev_b32_e32 v54, 16, v54
	v_lshlrev_b32_e32 v55, 16, v55
	v_lshlrev_b32_e32 v52, 16, v52
	v_lshlrev_b32_e32 v49, 16, v49
	v_lshlrev_b32_e32 v50, 16, v50
	v_lshlrev_b32_e32 v48, 16, v48
	v_lshlrev_b32_e32 v46, 16, v46
	v_lshlrev_b32_e32 v47, 16, v47
	v_lshlrev_b32_e32 v43, 16, v43
	v_lshlrev_b32_e32 v40, 16, v40
	v_lshlrev_b32_e32 v41, 16, v41
	v_lshlrev_b32_e32 v39, 16, v39
	v_lshlrev_b32_e32 v37, 16, v37
	v_lshlrev_b32_e32 v38, 16, v38
	v_lshlrev_b32_e32 v32, 16, v32
	v_lshlrev_b32_e32 v29, 16, v29
	v_lshlrev_b32_e32 v30, 16, v30
	v_lshlrev_b32_e32 v28, 16, v28
	v_lshlrev_b32_e32 v26, 16, v26
	v_lshlrev_b32_e32 v27, 16, v27
	v_lshlrev_b32_e32 v24, 16, v24
	v_lshlrev_b32_e32 v21, 16, v21
	v_lshlrev_b32_e32 v22, 16, v22
	v_lshlrev_b32_e32 v1, 16, v100
	s_waitcnt vmcnt(2)
	v_mul_f32_e32 v80, v72, v36
	v_readlane_b32 s49, v253, 43
	v_readlane_b32 s50, v253, 44
	v_mov_b32_dpp v80, v80 quad_perm:[1,0,3,2] row_mask:0xf bank_mask:0xf bound_ctrl:1
	v_fmac_f32_e32 v80, v72, v36
	v_readlane_b32 s51, v253, 45
	v_readlane_b32 s52, v253, 46
	v_add_f32_dpp v72, v80, v80 quad_perm:[2,3,0,1] row_mask:0xf bank_mask:0xf bound_ctrl:1
	v_readlane_b32 s53, v253, 47
	v_readlane_b32 s54, v253, 48
	v_add_f32_dpp v72, v72, v72 row_half_mirror row_mask:0xf bank_mask:0xf bound_ctrl:1
	v_readlane_b32 s55, v253, 49
	v_readlane_b32 s56, v253, 50
	v_add_f32_dpp v72, v72, v72 row_mirror row_mask:0xf bank_mask:0xf bound_ctrl:1
	v_readlane_b32 s57, v253, 51
	v_readlane_b32 s5, v72, 16
	v_readlane_b32 s4, v72, 0
	v_readlane_b32 s58, v253, 52
	v_mov_b32_e32 v80, s5
	v_readlane_b32 s5, v72, 48
	v_add_f32_e32 v80, s4, v80
	v_readlane_b32 s4, v72, 32
	v_mov_b32_e32 v72, s5
	v_readlane_b32 s59, v253, 53
	v_add_f32_e32 v72, s4, v72
	v_add_f32_e32 v72, v80, v72
	v_add_f32_dpp v80, v65, v65 quad_perm:[1,0,3,2] row_mask:0xf bank_mask:0xf bound_ctrl:1
	s_nop 1
	v_add_f32_dpp v80, v80, v80 quad_perm:[2,3,0,1] row_mask:0xf bank_mask:0xf bound_ctrl:1
	s_nop 1
	v_add_f32_dpp v80, v80, v80 row_half_mirror row_mask:0xf bank_mask:0xf bound_ctrl:1
	s_nop 1
	v_add_f32_dpp v80, v80, v80 row_mirror row_mask:0xf bank_mask:0xf bound_ctrl:1
	s_nop 0
	v_readlane_b32 s13, v80, 16
	v_readlane_b32 s14, v80, 48
	v_readlane_b32 s4, v80, 0
	v_readlane_b32 s5, v80, 32
	v_mov_b32_e32 v90, s13
	v_mov_b32_e32 v91, s14
	v_pk_add_f32 v[90:91], s[4:5], v[90:91]
	s_nop 0
	v_add_f32_e32 v80, v90, v91
	v_fmac_f32_e32 v65, 0xbc800000, v80
	v_mul_f32_e32 v80, v65, v65
	s_nop 1
	v_mov_b32_dpp v80, v80 quad_perm:[1,0,3,2] row_mask:0xf bank_mask:0xf bound_ctrl:1
	v_fmac_f32_e32 v80, v65, v65
	s_nop 1
	v_add_f32_dpp v80, v80, v80 quad_perm:[2,3,0,1] row_mask:0xf bank_mask:0xf bound_ctrl:1
	s_nop 1
	v_add_f32_dpp v80, v80, v80 row_half_mirror row_mask:0xf bank_mask:0xf bound_ctrl:1
	s_nop 1
	v_add_f32_dpp v80, v80, v80 row_mirror row_mask:0xf bank_mask:0xf bound_ctrl:1
	s_nop 0
	v_readlane_b32 s13, v80, 16
	v_readlane_b32 s14, v80, 48
	v_readlane_b32 s4, v80, 0
	v_readlane_b32 s5, v80, 32
	v_mov_b32_e32 v90, s13
	v_mov_b32_e32 v91, s14
	v_pk_add_f32 v[90:91], s[4:5], v[90:91]
	s_mov_b32 s4, 0x3a27c5ac
	v_mov_b32_e32 v92, v90
	v_mov_b32_e32 v14, v91
	v_pk_add_f32 v[90:91], v[92:93], v[14:15]
	v_mov_b64_e32 v[14:15], s[4:5]
	v_pk_fma_f32 v[90:91], v[90:91], s[46:47], v[14:15] op_sel_hi:[1,0,0]
	s_nop 0
	v_mul_f32_e32 v80, 0x4b800000, v91
	v_cmp_gt_f32_e64 s[4:5], s44, v91
	v_cmp_gt_f32_e32 vcc, s44, v90
	s_nop 0
	v_cndmask_b32_e64 v80, v91, v80, s[4:5]
	v_rsq_f32_e32 v80, v80
	s_nop 0
	v_mul_f32_e32 v86, 0x45800000, v80
	v_cndmask_b32_e64 v80, v80, v86, s[4:5]
	v_mul_f32_e32 v66, v66, v80
	s_waitcnt vmcnt(0)
	v_fma_f32 v66, v35, v66, v34
	v_fmac_f32_e32 v66, v72, v64
	v_mul_f32_e32 v18, v18, v66
	v_cvt_pk_bf16_f32 v18, v18, s0
	ds_write_b16 v45, v18 offset:8192
	v_mul_f32_e32 v18, 0x4b800000, v90
	v_cndmask_b32_e32 v18, v90, v18, vcc
	v_rsq_f32_e32 v18, v18
	s_nop 0
	v_mul_f32_e32 v64, 0x45800000, v18
	v_cndmask_b32_e32 v18, v18, v64, vcc
	v_mul_f32_e32 v64, v67, v68
	v_mul_f32_e32 v18, v65, v18
	v_mul_f32_e32 v65, v64, v36
	v_fma_f32 v18, v35, v18, v34
	s_nop 0
	v_mov_b32_dpp v65, v65 quad_perm:[1,0,3,2] row_mask:0xf bank_mask:0xf bound_ctrl:1
	v_fmac_f32_e32 v65, v64, v36
	s_nop 1
	v_add_f32_dpp v64, v65, v65 quad_perm:[2,3,0,1] row_mask:0xf bank_mask:0xf bound_ctrl:1
	s_nop 1
	v_add_f32_dpp v64, v64, v64 row_half_mirror row_mask:0xf bank_mask:0xf bound_ctrl:1
	s_nop 1
	v_add_f32_dpp v64, v64, v64 row_mirror row_mask:0xf bank_mask:0xf bound_ctrl:1
	s_nop 0
	v_readlane_b32 s5, v64, 16
	v_readlane_b32 s4, v64, 0
	s_nop 0
	v_mov_b32_e32 v65, s5
	v_readlane_b32 s5, v64, 48
	v_add_f32_e32 v65, s4, v65
	v_readlane_b32 s4, v64, 32
	v_mov_b32_e32 v64, s5
	s_nop 0
	v_add_f32_e32 v64, s4, v64
	v_add_f32_e32 v64, v65, v64
	v_fmac_f32_e32 v18, v64, v69
	v_mul_f32_e32 v18, v19, v18
	v_cvt_pk_bf16_f32 v18, v18, s0
	ds_write_b16 v45, v18 offset:8704
	v_mul_f32_e32 v64, v75, v76
	v_add_f32_dpp v18, v71, v71 quad_perm:[1,0,3,2] row_mask:0xf bank_mask:0xf bound_ctrl:1
	v_mul_f32_e32 v65, v64, v36
	s_nop 0
	v_add_f32_dpp v18, v18, v18 quad_perm:[2,3,0,1] row_mask:0xf bank_mask:0xf bound_ctrl:1
	v_mov_b32_dpp v65, v65 quad_perm:[1,0,3,2] row_mask:0xf bank_mask:0xf bound_ctrl:1
	v_fmac_f32_e32 v65, v64, v36
	v_add_f32_dpp v18, v18, v18 row_half_mirror row_mask:0xf bank_mask:0xf bound_ctrl:1
	s_nop 0
	v_add_f32_dpp v64, v65, v65 quad_perm:[2,3,0,1] row_mask:0xf bank_mask:0xf bound_ctrl:1
	v_add_f32_dpp v18, v18, v18 row_mirror row_mask:0xf bank_mask:0xf bound_ctrl:1
	s_nop 0
	v_readlane_b32 s13, v18, 16
	v_readlane_b32 s14, v18, 48
	v_readlane_b32 s4, v18, 0
	v_readlane_b32 s5, v18, 32
	v_mov_b32_e32 v18, s13
	v_mov_b32_e32 v19, s14
	v_pk_add_f32 v[18:19], s[4:5], v[18:19]
	v_add_f32_dpp v64, v64, v64 row_half_mirror row_mask:0xf bank_mask:0xf bound_ctrl:1
	v_add_f32_e32 v18, v18, v19
	v_fmac_f32_e32 v71, 0xbc800000, v18
	v_mul_f32_e32 v18, v71, v71
	v_add_f32_dpp v64, v64, v64 row_mirror row_mask:0xf bank_mask:0xf bound_ctrl:1
	s_nop 0
	v_mov_b32_dpp v18, v18 quad_perm:[1,0,3,2] row_mask:0xf bank_mask:0xf bound_ctrl:1
	v_fmac_f32_e32 v18, v71, v71
	s_nop 1
	v_add_f32_dpp v18, v18, v18 quad_perm:[2,3,0,1] row_mask:0xf bank_mask:0xf bound_ctrl:1
	s_nop 1
	v_add_f32_dpp v18, v18, v18 row_half_mirror row_mask:0xf bank_mask:0xf bound_ctrl:1
	s_nop 1
	v_add_f32_dpp v18, v18, v18 row_mirror row_mask:0xf bank_mask:0xf bound_ctrl:1
	s_nop 0
	v_readlane_b32 s13, v18, 16
	v_readlane_b32 s14, v18, 48
	v_readlane_b32 s4, v18, 0
	v_readlane_b32 s5, v18, 32
	v_mov_b32_e32 v18, s13
	v_mov_b32_e32 v19, s14
	v_pk_add_f32 v[18:19], s[4:5], v[18:19]
	v_readlane_b32 s5, v64, 16
	v_readlane_b32 s4, v64, 0
	v_mov_b32_e32 v67, v18
	v_mov_b32_e32 v65, s5
	v_readlane_b32 s5, v64, 48
	v_add_f32_e32 v65, s4, v65
	v_readlane_b32 s4, v64, 32
	v_mov_b32_e32 v64, s5
	s_nop 0
	v_add_f32_e32 v64, s4, v64
	v_add_f32_e32 v68, v65, v64
	s_nop 0
	v_add_f32_dpp v64, v79, v79 quad_perm:[1,0,3,2] row_mask:0xf bank_mask:0xf bound_ctrl:1
	s_nop 1
	v_add_f32_dpp v64, v64, v64 quad_perm:[2,3,0,1] row_mask:0xf bank_mask:0xf bound_ctrl:1
	s_nop 1
	v_add_f32_dpp v64, v64, v64 row_half_mirror row_mask:0xf bank_mask:0xf bound_ctrl:1
	s_nop 1
	v_add_f32_dpp v64, v64, v64 row_mirror row_mask:0xf bank_mask:0xf bound_ctrl:1
	s_nop 0
	v_readlane_b32 s13, v64, 16
	v_readlane_b32 s14, v64, 48
	v_readlane_b32 s4, v64, 0
	v_readlane_b32 s5, v64, 32
	v_mov_b32_e32 v64, s13
	v_mov_b32_e32 v65, s14
	v_pk_add_f32 v[64:65], s[4:5], v[64:65]
	s_nop 0
	v_add_f32_e32 v64, v64, v65
	v_fmac_f32_e32 v79, 0xbc800000, v64
	v_mul_f32_e32 v64, v79, v79
	s_nop 1
	v_mov_b32_dpp v64, v64 quad_perm:[1,0,3,2] row_mask:0xf bank_mask:0xf bound_ctrl:1
	v_fmac_f32_e32 v64, v79, v79
	s_nop 1
	v_add_f32_dpp v64, v64, v64 quad_perm:[2,3,0,1] row_mask:0xf bank_mask:0xf bound_ctrl:1
	s_nop 1
	v_add_f32_dpp v64, v64, v64 row_half_mirror row_mask:0xf bank_mask:0xf bound_ctrl:1
	s_nop 1
	v_add_f32_dpp v64, v64, v64 row_mirror row_mask:0xf bank_mask:0xf bound_ctrl:1
	s_nop 0
	v_readlane_b32 s13, v64, 16
	v_readlane_b32 s14, v64, 48
	v_readlane_b32 s4, v64, 0
	v_readlane_b32 s5, v64, 32
	v_mov_b32_e32 v64, s13
	v_mov_b32_e32 v65, s14
	v_pk_add_f32 v[64:65], s[4:5], v[64:65]
	s_nop 0
	v_mov_b32_e32 v66, v64
	v_mov_b32_e32 v18, v65
	v_pk_add_f32 v[18:19], v[66:67], v[18:19]
	s_nop 0
	v_pk_fma_f32 v[18:19], v[18:19], s[46:47], v[14:15] op_sel_hi:[1,0,0]
	s_nop 0
	v_mul_f32_e32 v64, 0x4b800000, v19
	v_cmp_gt_f32_e64 s[4:5], s44, v19
	v_cmp_gt_f32_e32 vcc, s44, v18
	s_nop 0
	v_cndmask_b32_e64 v19, v19, v64, s[4:5]
	v_rsq_f32_e32 v19, v19
	s_nop 0
	v_mul_f32_e32 v64, 0x45800000, v19
	v_cndmask_b32_e64 v19, v19, v64, s[4:5]
	v_mul_f32_e32 v19, v71, v19
	v_fma_f32 v19, v35, v19, v34
	v_fmac_f32_e32 v19, v68, v77
	v_mul_f32_e32 v16, v16, v19
	v_cvt_pk_bf16_f32 v16, v16, s0
	ds_write_b16 v45, v16 offset:9216
	v_mul_f32_e32 v16, 0x4b800000, v18
	v_cndmask_b32_e32 v16, v18, v16, vcc
	v_rsq_f32_e32 v16, v16
	s_nop 0
	v_mul_f32_e32 v18, 0x45800000, v16
	v_cndmask_b32_e32 v16, v16, v18, vcc
	v_mul_f32_e32 v18, v81, v82
	v_mul_f32_e32 v19, v18, v36
	v_mul_f32_e32 v16, v79, v16
	v_fma_f32 v16, v35, v16, v34
	v_mov_b32_dpp v19, v19 quad_perm:[1,0,3,2] row_mask:0xf bank_mask:0xf bound_ctrl:1
	v_fmac_f32_e32 v19, v18, v36
	s_nop 1
	v_add_f32_dpp v18, v19, v19 quad_perm:[2,3,0,1] row_mask:0xf bank_mask:0xf bound_ctrl:1
	s_nop 1
	v_add_f32_dpp v18, v18, v18 row_half_mirror row_mask:0xf bank_mask:0xf bound_ctrl:1
	s_nop 1
	v_add_f32_dpp v18, v18, v18 row_mirror row_mask:0xf bank_mask:0xf bound_ctrl:1
	s_nop 0
	v_readlane_b32 s5, v18, 16
	v_readlane_b32 s4, v18, 0
	s_nop 0
	v_mov_b32_e32 v19, s5
	v_readlane_b32 s5, v18, 48
	v_add_f32_e32 v19, s4, v19
	v_readlane_b32 s4, v18, 32
	v_mov_b32_e32 v18, s5
	s_nop 0
	v_add_f32_e32 v18, s4, v18
	v_add_f32_e32 v18, v19, v18
	v_fmac_f32_e32 v16, v18, v83
	v_mul_f32_e32 v16, v17, v16
	v_cvt_pk_bf16_f32 v16, v16, s0
	ds_write_b16 v45, v16 offset:9728
	v_mul_f32_e32 v18, v87, v88
	v_add_f32_dpp v16, v85, v85 quad_perm:[1,0,3,2] row_mask:0xf bank_mask:0xf bound_ctrl:1
	v_mul_f32_e32 v19, v18, v36
	s_nop 0
	v_add_f32_dpp v16, v16, v16 quad_perm:[2,3,0,1] row_mask:0xf bank_mask:0xf bound_ctrl:1
	v_mov_b32_dpp v19, v19 quad_perm:[1,0,3,2] row_mask:0xf bank_mask:0xf bound_ctrl:1
	v_fmac_f32_e32 v19, v18, v36
	v_add_f32_dpp v16, v16, v16 row_half_mirror row_mask:0xf bank_mask:0xf bound_ctrl:1
	s_nop 0
	v_add_f32_dpp v18, v19, v19 quad_perm:[2,3,0,1] row_mask:0xf bank_mask:0xf bound_ctrl:1
	v_add_f32_dpp v16, v16, v16 row_mirror row_mask:0xf bank_mask:0xf bound_ctrl:1
	s_nop 0
	v_readlane_b32 s13, v16, 16
	v_readlane_b32 s14, v16, 48
	v_readlane_b32 s4, v16, 0
	v_readlane_b32 s5, v16, 32
	v_mov_b32_e32 v16, s13
	v_mov_b32_e32 v17, s14
	v_pk_add_f32 v[16:17], s[4:5], v[16:17]
	v_add_f32_dpp v18, v18, v18 row_half_mirror row_mask:0xf bank_mask:0xf bound_ctrl:1
	v_add_f32_e32 v16, v16, v17
	v_fmac_f32_e32 v85, 0xbc800000, v16
	v_mul_f32_e32 v16, v85, v85
	v_add_f32_dpp v18, v18, v18 row_mirror row_mask:0xf bank_mask:0xf bound_ctrl:1
	s_nop 0
	v_mov_b32_dpp v16, v16 quad_perm:[1,0,3,2] row_mask:0xf bank_mask:0xf bound_ctrl:1
	v_fmac_f32_e32 v16, v85, v85
	s_nop 1
	v_add_f32_dpp v16, v16, v16 quad_perm:[2,3,0,1] row_mask:0xf bank_mask:0xf bound_ctrl:1
	s_nop 1
	v_add_f32_dpp v16, v16, v16 row_half_mirror row_mask:0xf bank_mask:0xf bound_ctrl:1
	s_nop 1
	v_add_f32_dpp v16, v16, v16 row_mirror row_mask:0xf bank_mask:0xf bound_ctrl:1
	s_nop 0
	v_readlane_b32 s13, v16, 16
	v_readlane_b32 s14, v16, 48
	v_readlane_b32 s4, v16, 0
	v_readlane_b32 s5, v16, 32
	v_mov_b32_e32 v16, s13
	v_mov_b32_e32 v17, s14
	v_pk_add_f32 v[16:17], s[4:5], v[16:17]
	v_readlane_b32 s5, v18, 16
	v_readlane_b32 s4, v18, 0
	v_mov_b32_e32 v65, v16
	v_mov_b32_e32 v19, s5
	v_readlane_b32 s5, v18, 48
	v_add_f32_e32 v19, s4, v19
	v_readlane_b32 s4, v18, 32
	v_mov_b32_e32 v18, s5
	s_nop 0
	v_add_f32_e32 v18, s4, v18
	v_add_f32_e32 v66, v19, v18
	s_nop 0
	v_add_f32_dpp v18, v78, v78 quad_perm:[1,0,3,2] row_mask:0xf bank_mask:0xf bound_ctrl:1
	s_nop 1
	v_add_f32_dpp v18, v18, v18 quad_perm:[2,3,0,1] row_mask:0xf bank_mask:0xf bound_ctrl:1
	s_nop 1
	v_add_f32_dpp v18, v18, v18 row_half_mirror row_mask:0xf bank_mask:0xf bound_ctrl:1
	s_nop 1
	v_add_f32_dpp v18, v18, v18 row_mirror row_mask:0xf bank_mask:0xf bound_ctrl:1
	s_nop 0
	v_readlane_b32 s13, v18, 16
	v_readlane_b32 s14, v18, 48
	v_readlane_b32 s4, v18, 0
	v_readlane_b32 s5, v18, 32
	v_mov_b32_e32 v18, s13
	v_mov_b32_e32 v19, s14
	v_pk_add_f32 v[18:19], s[4:5], v[18:19]
	s_nop 0
	v_add_f32_e32 v18, v18, v19
	v_fmac_f32_e32 v78, 0xbc800000, v18
	v_mul_f32_e32 v18, v78, v78
	s_nop 1
	v_mov_b32_dpp v18, v18 quad_perm:[1,0,3,2] row_mask:0xf bank_mask:0xf bound_ctrl:1
	v_fmac_f32_e32 v18, v78, v78
	s_nop 1
	v_add_f32_dpp v18, v18, v18 quad_perm:[2,3,0,1] row_mask:0xf bank_mask:0xf bound_ctrl:1
	s_nop 1
	v_add_f32_dpp v18, v18, v18 row_half_mirror row_mask:0xf bank_mask:0xf bound_ctrl:1
	s_nop 1
	v_add_f32_dpp v18, v18, v18 row_mirror row_mask:0xf bank_mask:0xf bound_ctrl:1
	s_nop 0
	v_readlane_b32 s13, v18, 16
	v_readlane_b32 s14, v18, 48
	v_readlane_b32 s4, v18, 0
	v_readlane_b32 s5, v18, 32
	v_mov_b32_e32 v18, s13
	v_mov_b32_e32 v19, s14
	v_pk_add_f32 v[18:19], s[4:5], v[18:19]
	s_nop 0
	v_mov_b32_e32 v64, v18
	v_mov_b32_e32 v16, v19
	v_pk_add_f32 v[16:17], v[64:65], v[16:17]
	s_nop 0
	v_pk_fma_f32 v[16:17], v[16:17], s[46:47], v[14:15] op_sel_hi:[1,0,0]
	s_nop 0
	v_mul_f32_e32 v18, 0x4b800000, v17
	v_cmp_gt_f32_e64 s[4:5], s44, v17
	v_cmp_gt_f32_e32 vcc, s44, v16
	s_nop 0
	v_cndmask_b32_e64 v17, v17, v18, s[4:5]
	v_rsq_f32_e32 v17, v17
	s_nop 0
	v_mul_f32_e32 v18, 0x45800000, v17
	v_cndmask_b32_e64 v17, v17, v18, s[4:5]
	v_mul_f32_e32 v17, v85, v17
	v_fma_f32 v17, v35, v17, v34
	v_fmac_f32_e32 v17, v66, v84
	v_mul_f32_e32 v12, v12, v17
	v_cvt_pk_bf16_f32 v12, v12, s0
	ds_write_b16 v45, v12 offset:10240
	v_mul_f32_e32 v12, 0x4b800000, v16
	v_cndmask_b32_e32 v12, v16, v12, vcc
	v_rsq_f32_e32 v12, v12
	s_nop 0
	v_mul_f32_e32 v16, 0x45800000, v12
	v_cndmask_b32_e32 v12, v12, v16, vcc
	v_mul_f32_e32 v16, v74, v73
	v_mul_f32_e32 v17, v16, v36
	v_mul_f32_e32 v12, v78, v12
	v_fma_f32 v12, v35, v12, v34
	v_mov_b32_dpp v17, v17 quad_perm:[1,0,3,2] row_mask:0xf bank_mask:0xf bound_ctrl:1
	v_fmac_f32_e32 v17, v16, v36
	s_nop 1
	v_add_f32_dpp v16, v17, v17 quad_perm:[2,3,0,1] row_mask:0xf bank_mask:0xf bound_ctrl:1
	s_nop 1
	v_add_f32_dpp v16, v16, v16 row_half_mirror row_mask:0xf bank_mask:0xf bound_ctrl:1
	s_nop 1
	v_add_f32_dpp v16, v16, v16 row_mirror row_mask:0xf bank_mask:0xf bound_ctrl:1
	s_nop 0
	v_readlane_b32 s5, v16, 16
	v_readlane_b32 s4, v16, 0
	s_nop 0
	v_mov_b32_e32 v17, s5
	v_readlane_b32 s5, v16, 48
	v_add_f32_e32 v17, s4, v17
	v_readlane_b32 s4, v16, 32
	v_mov_b32_e32 v16, s5
	s_nop 0
	v_add_f32_e32 v16, s4, v16
	v_add_f32_e32 v16, v17, v16
	v_fmac_f32_e32 v12, v16, v70
	v_mul_f32_e32 v12, v13, v12
	v_cvt_pk_bf16_f32 v12, v12, s0
	ds_write_b16 v45, v12 offset:10752
	v_mul_f32_e32 v16, v63, v62
	v_add_f32_dpp v12, v61, v61 quad_perm:[1,0,3,2] row_mask:0xf bank_mask:0xf bound_ctrl:1
	v_mul_f32_e32 v17, v16, v36
	s_nop 0
	v_add_f32_dpp v12, v12, v12 quad_perm:[2,3,0,1] row_mask:0xf bank_mask:0xf bound_ctrl:1
	v_mov_b32_dpp v17, v17 quad_perm:[1,0,3,2] row_mask:0xf bank_mask:0xf bound_ctrl:1
	v_fmac_f32_e32 v17, v16, v36
	v_add_f32_dpp v12, v12, v12 row_half_mirror row_mask:0xf bank_mask:0xf bound_ctrl:1
	s_nop 0
	v_add_f32_dpp v16, v17, v17 quad_perm:[2,3,0,1] row_mask:0xf bank_mask:0xf bound_ctrl:1
	v_add_f32_dpp v12, v12, v12 row_mirror row_mask:0xf bank_mask:0xf bound_ctrl:1
	s_nop 0
	v_readlane_b32 s13, v12, 16
	v_readlane_b32 s14, v12, 48
	v_readlane_b32 s4, v12, 0
	v_readlane_b32 s5, v12, 32
	v_mov_b32_e32 v12, s13
	v_mov_b32_e32 v13, s14
	v_pk_add_f32 v[12:13], s[4:5], v[12:13]
	v_add_f32_dpp v16, v16, v16 row_half_mirror row_mask:0xf bank_mask:0xf bound_ctrl:1
	v_add_f32_e32 v12, v12, v13
	v_fmac_f32_e32 v61, 0xbc800000, v12
	v_mul_f32_e32 v12, v61, v61
	v_add_f32_dpp v16, v16, v16 row_mirror row_mask:0xf bank_mask:0xf bound_ctrl:1
	s_nop 0
	v_mov_b32_dpp v12, v12 quad_perm:[1,0,3,2] row_mask:0xf bank_mask:0xf bound_ctrl:1
	v_fmac_f32_e32 v12, v61, v61
	s_nop 1
	v_add_f32_dpp v12, v12, v12 quad_perm:[2,3,0,1] row_mask:0xf bank_mask:0xf bound_ctrl:1
	s_nop 1
	v_add_f32_dpp v12, v12, v12 row_half_mirror row_mask:0xf bank_mask:0xf bound_ctrl:1
	s_nop 1
	v_add_f32_dpp v12, v12, v12 row_mirror row_mask:0xf bank_mask:0xf bound_ctrl:1
	s_nop 0
	v_readlane_b32 s13, v12, 16
	v_readlane_b32 s14, v12, 48
	v_readlane_b32 s4, v12, 0
	v_readlane_b32 s5, v12, 32
	v_mov_b32_e32 v12, s13
	v_mov_b32_e32 v13, s14
	v_pk_add_f32 v[12:13], s[4:5], v[12:13]
	v_readlane_b32 s5, v16, 16
	v_readlane_b32 s4, v16, 0
	v_mov_b32_e32 v19, v12
	v_mov_b32_e32 v17, s5
	v_readlane_b32 s5, v16, 48
	v_add_f32_e32 v17, s4, v17
	v_readlane_b32 s4, v16, 32
	v_mov_b32_e32 v16, s5
	s_nop 0
	v_add_f32_e32 v16, s4, v16
	v_add_f32_e32 v62, v17, v16
	s_nop 0
	v_add_f32_dpp v16, v59, v59 quad_perm:[1,0,3,2] row_mask:0xf bank_mask:0xf bound_ctrl:1
	s_nop 1
	v_add_f32_dpp v16, v16, v16 quad_perm:[2,3,0,1] row_mask:0xf bank_mask:0xf bound_ctrl:1
	s_nop 1
	v_add_f32_dpp v16, v16, v16 row_half_mirror row_mask:0xf bank_mask:0xf bound_ctrl:1
	s_nop 1
	v_add_f32_dpp v16, v16, v16 row_mirror row_mask:0xf bank_mask:0xf bound_ctrl:1
	s_nop 0
	v_readlane_b32 s13, v16, 16
	v_readlane_b32 s14, v16, 48
	v_readlane_b32 s4, v16, 0
	v_readlane_b32 s5, v16, 32
	v_mov_b32_e32 v16, s13
	v_mov_b32_e32 v17, s14
	v_pk_add_f32 v[16:17], s[4:5], v[16:17]
	s_nop 0
	v_add_f32_e32 v16, v16, v17
	v_fmac_f32_e32 v59, 0xbc800000, v16
	v_mul_f32_e32 v16, v59, v59
	s_nop 1
	v_mov_b32_dpp v16, v16 quad_perm:[1,0,3,2] row_mask:0xf bank_mask:0xf bound_ctrl:1
	v_fmac_f32_e32 v16, v59, v59
	s_nop 1
	v_add_f32_dpp v16, v16, v16 quad_perm:[2,3,0,1] row_mask:0xf bank_mask:0xf bound_ctrl:1
	s_nop 1
	v_add_f32_dpp v16, v16, v16 row_half_mirror row_mask:0xf bank_mask:0xf bound_ctrl:1
	s_nop 1
	v_add_f32_dpp v16, v16, v16 row_mirror row_mask:0xf bank_mask:0xf bound_ctrl:1
	s_nop 0
	v_readlane_b32 s13, v16, 16
	v_readlane_b32 s14, v16, 48
	v_readlane_b32 s4, v16, 0
	v_readlane_b32 s5, v16, 32
	v_mov_b32_e32 v16, s13
	v_mov_b32_e32 v17, s14
	v_pk_add_f32 v[16:17], s[4:5], v[16:17]
	s_nop 0
	v_mov_b32_e32 v18, v16
	v_mov_b32_e32 v12, v17
	v_pk_add_f32 v[12:13], v[18:19], v[12:13]
	s_nop 0
	v_pk_fma_f32 v[12:13], v[12:13], s[46:47], v[14:15] op_sel_hi:[1,0,0]
	s_nop 0
	v_mul_f32_e32 v16, 0x4b800000, v13
	v_cmp_gt_f32_e64 s[4:5], s44, v13
	v_cmp_gt_f32_e32 vcc, s44, v12
	s_nop 0
	v_cndmask_b32_e64 v13, v13, v16, s[4:5]
	v_rsq_f32_e32 v13, v13
	s_nop 0
	v_mul_f32_e32 v16, 0x45800000, v13
	v_cndmask_b32_e64 v13, v13, v16, s[4:5]
	v_mul_f32_e32 v13, v61, v13
	v_fma_f32 v13, v35, v13, v34
	v_fmac_f32_e32 v13, v62, v60
	v_mul_f32_e32 v10, v10, v13
	v_cvt_pk_bf16_f32 v10, v10, s0
	ds_write_b16 v45, v10 offset:11264
	v_mul_f32_e32 v10, 0x4b800000, v12
	v_cndmask_b32_e32 v10, v12, v10, vcc
	v_rsq_f32_e32 v10, v10
	s_nop 0
	v_mul_f32_e32 v12, 0x45800000, v10
	v_cndmask_b32_e32 v10, v10, v12, vcc
	v_mul_f32_e32 v12, v58, v57
	v_mul_f32_e32 v13, v12, v36
	v_mul_f32_e32 v10, v59, v10
	v_fma_f32 v10, v35, v10, v34
	v_mov_b32_dpp v13, v13 quad_perm:[1,0,3,2] row_mask:0xf bank_mask:0xf bound_ctrl:1
	v_fmac_f32_e32 v13, v12, v36
	s_nop 1
	v_add_f32_dpp v12, v13, v13 quad_perm:[2,3,0,1] row_mask:0xf bank_mask:0xf bound_ctrl:1
	s_nop 1
	v_add_f32_dpp v12, v12, v12 row_half_mirror row_mask:0xf bank_mask:0xf bound_ctrl:1
	s_nop 1
	v_add_f32_dpp v12, v12, v12 row_mirror row_mask:0xf bank_mask:0xf bound_ctrl:1
	s_nop 0
	v_readlane_b32 s5, v12, 16
	v_readlane_b32 s4, v12, 0
	s_nop 0
	v_mov_b32_e32 v13, s5
	v_readlane_b32 s5, v12, 48
	v_add_f32_e32 v13, s4, v13
	v_readlane_b32 s4, v12, 32
	v_mov_b32_e32 v12, s5
	s_nop 0
	v_add_f32_e32 v12, s4, v12
	v_add_f32_e32 v12, v13, v12
	v_fmac_f32_e32 v10, v12, v56
	v_mul_f32_e32 v10, v11, v10
	v_cvt_pk_bf16_f32 v10, v10, s0
	ds_write_b16 v45, v10 offset:11776
	v_mul_f32_e32 v12, v55, v54
	v_add_f32_dpp v10, v53, v53 quad_perm:[1,0,3,2] row_mask:0xf bank_mask:0xf bound_ctrl:1
	v_mul_f32_e32 v13, v12, v36
	s_nop 0
	v_add_f32_dpp v10, v10, v10 quad_perm:[2,3,0,1] row_mask:0xf bank_mask:0xf bound_ctrl:1
	v_mov_b32_dpp v13, v13 quad_perm:[1,0,3,2] row_mask:0xf bank_mask:0xf bound_ctrl:1
	v_fmac_f32_e32 v13, v12, v36
	v_add_f32_dpp v10, v10, v10 row_half_mirror row_mask:0xf bank_mask:0xf bound_ctrl:1
	s_nop 0
	v_add_f32_dpp v12, v13, v13 quad_perm:[2,3,0,1] row_mask:0xf bank_mask:0xf bound_ctrl:1
	v_add_f32_dpp v10, v10, v10 row_mirror row_mask:0xf bank_mask:0xf bound_ctrl:1
	s_nop 0
	v_readlane_b32 s13, v10, 16
	v_readlane_b32 s14, v10, 48
	v_readlane_b32 s4, v10, 0
	v_readlane_b32 s5, v10, 32
	v_mov_b32_e32 v10, s13
	v_mov_b32_e32 v11, s14
	v_pk_add_f32 v[10:11], s[4:5], v[10:11]
	v_add_f32_dpp v12, v12, v12 row_half_mirror row_mask:0xf bank_mask:0xf bound_ctrl:1
	v_add_f32_e32 v10, v10, v11
	v_fmac_f32_e32 v53, 0xbc800000, v10
	v_mul_f32_e32 v10, v53, v53
	v_add_f32_dpp v12, v12, v12 row_mirror row_mask:0xf bank_mask:0xf bound_ctrl:1
	s_nop 0
	v_mov_b32_dpp v10, v10 quad_perm:[1,0,3,2] row_mask:0xf bank_mask:0xf bound_ctrl:1
	v_fmac_f32_e32 v10, v53, v53
	s_nop 1
	v_add_f32_dpp v10, v10, v10 quad_perm:[2,3,0,1] row_mask:0xf bank_mask:0xf bound_ctrl:1
	s_nop 1
	v_add_f32_dpp v10, v10, v10 row_half_mirror row_mask:0xf bank_mask:0xf bound_ctrl:1
	s_nop 1
	v_add_f32_dpp v10, v10, v10 row_mirror row_mask:0xf bank_mask:0xf bound_ctrl:1
	s_nop 0
	v_readlane_b32 s13, v10, 16
	v_readlane_b32 s14, v10, 48
	v_readlane_b32 s4, v10, 0
	v_readlane_b32 s5, v10, 32
	v_mov_b32_e32 v10, s13
	v_mov_b32_e32 v11, s14
	v_pk_add_f32 v[10:11], s[4:5], v[10:11]
	v_readlane_b32 s5, v12, 16
	v_readlane_b32 s4, v12, 0
	v_mov_b32_e32 v17, v10
	v_mov_b32_e32 v13, s5
	v_readlane_b32 s5, v12, 48
	v_add_f32_e32 v13, s4, v13
	v_readlane_b32 s4, v12, 32
	v_mov_b32_e32 v12, s5
	s_nop 0
	v_add_f32_e32 v12, s4, v12
	v_add_f32_e32 v18, v13, v12
	s_nop 0
	v_add_f32_dpp v12, v51, v51 quad_perm:[1,0,3,2] row_mask:0xf bank_mask:0xf bound_ctrl:1
	s_nop 1
	v_add_f32_dpp v12, v12, v12 quad_perm:[2,3,0,1] row_mask:0xf bank_mask:0xf bound_ctrl:1
	s_nop 1
	v_add_f32_dpp v12, v12, v12 row_half_mirror row_mask:0xf bank_mask:0xf bound_ctrl:1
	s_nop 1
	v_add_f32_dpp v12, v12, v12 row_mirror row_mask:0xf bank_mask:0xf bound_ctrl:1
	s_nop 0
	v_readlane_b32 s13, v12, 16
	v_readlane_b32 s14, v12, 48
	v_readlane_b32 s4, v12, 0
	v_readlane_b32 s5, v12, 32
	v_mov_b32_e32 v12, s13
	v_mov_b32_e32 v13, s14
	v_pk_add_f32 v[12:13], s[4:5], v[12:13]
	s_nop 0
	v_add_f32_e32 v12, v12, v13
	v_fmac_f32_e32 v51, 0xbc800000, v12
	v_mul_f32_e32 v12, v51, v51
	s_nop 1
	v_mov_b32_dpp v12, v12 quad_perm:[1,0,3,2] row_mask:0xf bank_mask:0xf bound_ctrl:1
	v_fmac_f32_e32 v12, v51, v51
	s_nop 1
	v_add_f32_dpp v12, v12, v12 quad_perm:[2,3,0,1] row_mask:0xf bank_mask:0xf bound_ctrl:1
	s_nop 1
	v_add_f32_dpp v12, v12, v12 row_half_mirror row_mask:0xf bank_mask:0xf bound_ctrl:1
	s_nop 1
	v_add_f32_dpp v12, v12, v12 row_mirror row_mask:0xf bank_mask:0xf bound_ctrl:1
	s_nop 0
	v_readlane_b32 s13, v12, 16
	v_readlane_b32 s14, v12, 48
	v_readlane_b32 s4, v12, 0
	v_readlane_b32 s5, v12, 32
	v_mov_b32_e32 v12, s13
	v_mov_b32_e32 v13, s14
	v_pk_add_f32 v[12:13], s[4:5], v[12:13]
	s_nop 0
	v_mov_b32_e32 v16, v12
	v_mov_b32_e32 v10, v13
	v_pk_add_f32 v[10:11], v[16:17], v[10:11]
	s_nop 0
	v_pk_fma_f32 v[10:11], v[10:11], s[46:47], v[14:15] op_sel_hi:[1,0,0]
	s_nop 0
	v_mul_f32_e32 v12, 0x4b800000, v11
	v_cmp_gt_f32_e64 s[4:5], s44, v11
	v_cmp_gt_f32_e32 vcc, s44, v10
	s_nop 0
	v_cndmask_b32_e64 v11, v11, v12, s[4:5]
	v_rsq_f32_e32 v11, v11
	s_nop 0
	v_mul_f32_e32 v12, 0x45800000, v11
	v_cndmask_b32_e64 v11, v11, v12, s[4:5]
	v_mul_f32_e32 v11, v53, v11
	v_fma_f32 v11, v35, v11, v34
	v_fmac_f32_e32 v11, v18, v52
	v_mul_f32_e32 v8, v8, v11
	v_cvt_pk_bf16_f32 v8, v8, s0
	ds_write_b16 v45, v8 offset:12288
	v_mul_f32_e32 v8, 0x4b800000, v10
	v_cndmask_b32_e32 v8, v10, v8, vcc
	v_rsq_f32_e32 v8, v8
	s_nop 0
	v_mul_f32_e32 v10, 0x45800000, v8
	v_cndmask_b32_e32 v8, v8, v10, vcc
	v_mul_f32_e32 v10, v50, v49
	v_mul_f32_e32 v11, v10, v36
	v_mul_f32_e32 v8, v51, v8
	v_fma_f32 v8, v35, v8, v34
	v_mov_b32_dpp v11, v11 quad_perm:[1,0,3,2] row_mask:0xf bank_mask:0xf bound_ctrl:1
	v_fmac_f32_e32 v11, v10, v36
	s_nop 1
	v_add_f32_dpp v10, v11, v11 quad_perm:[2,3,0,1] row_mask:0xf bank_mask:0xf bound_ctrl:1
	s_nop 1
	v_add_f32_dpp v10, v10, v10 row_half_mirror row_mask:0xf bank_mask:0xf bound_ctrl:1
	s_nop 1
	v_add_f32_dpp v10, v10, v10 row_mirror row_mask:0xf bank_mask:0xf bound_ctrl:1
	s_nop 0
	v_readlane_b32 s5, v10, 16
	v_readlane_b32 s4, v10, 0
	s_nop 0
	v_mov_b32_e32 v11, s5
	v_readlane_b32 s5, v10, 48
	v_add_f32_e32 v11, s4, v11
	v_readlane_b32 s4, v10, 32
	v_mov_b32_e32 v10, s5
	s_nop 0
	v_add_f32_e32 v10, s4, v10
	v_add_f32_e32 v10, v11, v10
	v_fmac_f32_e32 v8, v10, v48
	v_mul_f32_e32 v8, v9, v8
	v_cvt_pk_bf16_f32 v8, v8, s0
	ds_write_b16 v45, v8 offset:12800
	v_mul_f32_e32 v10, v47, v46
	v_add_f32_dpp v8, v44, v44 quad_perm:[1,0,3,2] row_mask:0xf bank_mask:0xf bound_ctrl:1
	v_mul_f32_e32 v11, v10, v36
	s_nop 0
	v_add_f32_dpp v8, v8, v8 quad_perm:[2,3,0,1] row_mask:0xf bank_mask:0xf bound_ctrl:1
	v_mov_b32_dpp v11, v11 quad_perm:[1,0,3,2] row_mask:0xf bank_mask:0xf bound_ctrl:1
	v_fmac_f32_e32 v11, v10, v36
	v_add_f32_dpp v8, v8, v8 row_half_mirror row_mask:0xf bank_mask:0xf bound_ctrl:1
	s_nop 0
	v_add_f32_dpp v10, v11, v11 quad_perm:[2,3,0,1] row_mask:0xf bank_mask:0xf bound_ctrl:1
	v_add_f32_dpp v8, v8, v8 row_mirror row_mask:0xf bank_mask:0xf bound_ctrl:1
	s_nop 0
	v_readlane_b32 s13, v8, 16
	v_readlane_b32 s14, v8, 48
	v_readlane_b32 s4, v8, 0
	v_readlane_b32 s5, v8, 32
	v_mov_b32_e32 v8, s13
	v_mov_b32_e32 v9, s14
	v_pk_add_f32 v[8:9], s[4:5], v[8:9]
	v_add_f32_dpp v10, v10, v10 row_half_mirror row_mask:0xf bank_mask:0xf bound_ctrl:1
	v_add_f32_e32 v8, v8, v9
	v_fmac_f32_e32 v44, 0xbc800000, v8
	v_mul_f32_e32 v8, v44, v44
	v_add_f32_dpp v10, v10, v10 row_mirror row_mask:0xf bank_mask:0xf bound_ctrl:1
	s_nop 0
	v_mov_b32_dpp v8, v8 quad_perm:[1,0,3,2] row_mask:0xf bank_mask:0xf bound_ctrl:1
	v_fmac_f32_e32 v8, v44, v44
	s_nop 1
	v_add_f32_dpp v8, v8, v8 quad_perm:[2,3,0,1] row_mask:0xf bank_mask:0xf bound_ctrl:1
	s_nop 1
	v_add_f32_dpp v8, v8, v8 row_half_mirror row_mask:0xf bank_mask:0xf bound_ctrl:1
	s_nop 1
	v_add_f32_dpp v8, v8, v8 row_mirror row_mask:0xf bank_mask:0xf bound_ctrl:1
	s_nop 0
	v_readlane_b32 s13, v8, 16
	v_readlane_b32 s14, v8, 48
	v_readlane_b32 s4, v8, 0
	v_readlane_b32 s5, v8, 32
	v_mov_b32_e32 v8, s13
	v_mov_b32_e32 v9, s14
	v_pk_add_f32 v[8:9], s[4:5], v[8:9]
	v_readlane_b32 s5, v10, 16
	v_readlane_b32 s4, v10, 0
	v_mov_b32_e32 v13, v8
	v_mov_b32_e32 v11, s5
	v_readlane_b32 s5, v10, 48
	v_add_f32_e32 v11, s4, v11
	v_readlane_b32 s4, v10, 32
	v_mov_b32_e32 v10, s5
	s_nop 0
	v_add_f32_e32 v10, s4, v10
	v_add_f32_e32 v16, v11, v10
	s_nop 0
	v_add_f32_dpp v10, v42, v42 quad_perm:[1,0,3,2] row_mask:0xf bank_mask:0xf bound_ctrl:1
	s_nop 1
	v_add_f32_dpp v10, v10, v10 quad_perm:[2,3,0,1] row_mask:0xf bank_mask:0xf bound_ctrl:1
	s_nop 1
	v_add_f32_dpp v10, v10, v10 row_half_mirror row_mask:0xf bank_mask:0xf bound_ctrl:1
	s_nop 1
	v_add_f32_dpp v10, v10, v10 row_mirror row_mask:0xf bank_mask:0xf bound_ctrl:1
	s_nop 0
	v_readlane_b32 s13, v10, 16
	v_readlane_b32 s14, v10, 48
	v_readlane_b32 s4, v10, 0
	v_readlane_b32 s5, v10, 32
	v_mov_b32_e32 v10, s13
	v_mov_b32_e32 v11, s14
	v_pk_add_f32 v[10:11], s[4:5], v[10:11]
	s_nop 0
	v_add_f32_e32 v10, v10, v11
	v_fmac_f32_e32 v42, 0xbc800000, v10
	v_mul_f32_e32 v10, v42, v42
	s_nop 1
	v_mov_b32_dpp v10, v10 quad_perm:[1,0,3,2] row_mask:0xf bank_mask:0xf bound_ctrl:1
	v_fmac_f32_e32 v10, v42, v42
	s_nop 1
	v_add_f32_dpp v10, v10, v10 quad_perm:[2,3,0,1] row_mask:0xf bank_mask:0xf bound_ctrl:1
	s_nop 1
	v_add_f32_dpp v10, v10, v10 row_half_mirror row_mask:0xf bank_mask:0xf bound_ctrl:1
	s_nop 1
	v_add_f32_dpp v10, v10, v10 row_mirror row_mask:0xf bank_mask:0xf bound_ctrl:1
	s_nop 0
	v_readlane_b32 s13, v10, 16
	v_readlane_b32 s14, v10, 48
	v_readlane_b32 s4, v10, 0
	v_readlane_b32 s5, v10, 32
	v_mov_b32_e32 v10, s13
	v_mov_b32_e32 v11, s14
	v_pk_add_f32 v[10:11], s[4:5], v[10:11]
	s_nop 0
	v_mov_b32_e32 v12, v10
	v_mov_b32_e32 v8, v11
	v_pk_add_f32 v[8:9], v[12:13], v[8:9]
	s_nop 0
	v_pk_fma_f32 v[8:9], v[8:9], s[46:47], v[14:15] op_sel_hi:[1,0,0]
	s_nop 0
	v_mul_f32_e32 v10, 0x4b800000, v9
	v_cmp_gt_f32_e64 s[4:5], s44, v9
	v_cmp_gt_f32_e32 vcc, s44, v8
	s_nop 0
	v_cndmask_b32_e64 v9, v9, v10, s[4:5]
	v_rsq_f32_e32 v9, v9
	s_nop 0
	v_mul_f32_e32 v10, 0x45800000, v9
	v_cndmask_b32_e64 v9, v9, v10, s[4:5]
	v_mul_f32_e32 v9, v44, v9
	v_fma_f32 v9, v35, v9, v34
	v_fmac_f32_e32 v9, v16, v43
	v_mul_f32_e32 v6, v6, v9
	v_cvt_pk_bf16_f32 v6, v6, s0
	ds_write_b16 v45, v6 offset:13312
	v_mul_f32_e32 v6, 0x4b800000, v8
	v_cndmask_b32_e32 v6, v8, v6, vcc
	v_rsq_f32_e32 v6, v6
	s_nop 0
	v_mul_f32_e32 v8, 0x45800000, v6
	v_cndmask_b32_e32 v6, v6, v8, vcc
	v_mul_f32_e32 v8, v41, v40
	v_mul_f32_e32 v9, v8, v36
	v_mul_f32_e32 v6, v42, v6
	v_fma_f32 v6, v35, v6, v34
	v_mov_b32_dpp v9, v9 quad_perm:[1,0,3,2] row_mask:0xf bank_mask:0xf bound_ctrl:1
	v_fmac_f32_e32 v9, v8, v36
	s_nop 1
	v_add_f32_dpp v8, v9, v9 quad_perm:[2,3,0,1] row_mask:0xf bank_mask:0xf bound_ctrl:1
	s_nop 1
	v_add_f32_dpp v8, v8, v8 row_half_mirror row_mask:0xf bank_mask:0xf bound_ctrl:1
	s_nop 1
	v_add_f32_dpp v8, v8, v8 row_mirror row_mask:0xf bank_mask:0xf bound_ctrl:1
	s_nop 0
	v_readlane_b32 s5, v8, 16
	v_readlane_b32 s4, v8, 0
	s_nop 0
	v_mov_b32_e32 v9, s5
	v_readlane_b32 s5, v8, 48
	v_add_f32_e32 v9, s4, v9
	v_readlane_b32 s4, v8, 32
	v_mov_b32_e32 v8, s5
	s_nop 0
	v_add_f32_e32 v8, s4, v8
	v_add_f32_e32 v8, v9, v8
	v_fmac_f32_e32 v6, v8, v39
	v_mul_f32_e32 v6, v7, v6
	v_cvt_pk_bf16_f32 v6, v6, s0
	ds_write_b16 v45, v6 offset:13824
	v_mul_f32_e32 v8, v38, v37
	v_add_f32_dpp v6, v33, v33 quad_perm:[1,0,3,2] row_mask:0xf bank_mask:0xf bound_ctrl:1
	v_mul_f32_e32 v9, v8, v36
	s_nop 0
	v_add_f32_dpp v6, v6, v6 quad_perm:[2,3,0,1] row_mask:0xf bank_mask:0xf bound_ctrl:1
	v_mov_b32_dpp v9, v9 quad_perm:[1,0,3,2] row_mask:0xf bank_mask:0xf bound_ctrl:1
	v_fmac_f32_e32 v9, v8, v36
	v_add_f32_dpp v6, v6, v6 row_half_mirror row_mask:0xf bank_mask:0xf bound_ctrl:1
	s_nop 0
	v_add_f32_dpp v8, v9, v9 quad_perm:[2,3,0,1] row_mask:0xf bank_mask:0xf bound_ctrl:1
	v_add_f32_dpp v6, v6, v6 row_mirror row_mask:0xf bank_mask:0xf bound_ctrl:1
	s_nop 0
	v_readlane_b32 s13, v6, 16
	v_readlane_b32 s14, v6, 48
	v_readlane_b32 s4, v6, 0
	v_readlane_b32 s5, v6, 32
	v_mov_b32_e32 v6, s13
	v_mov_b32_e32 v7, s14
	v_pk_add_f32 v[6:7], s[4:5], v[6:7]
	v_add_f32_dpp v8, v8, v8 row_half_mirror row_mask:0xf bank_mask:0xf bound_ctrl:1
	v_add_f32_e32 v6, v6, v7
	v_fmac_f32_e32 v33, 0xbc800000, v6
	v_mul_f32_e32 v6, v33, v33
	v_add_f32_dpp v8, v8, v8 row_mirror row_mask:0xf bank_mask:0xf bound_ctrl:1
	s_nop 0
	v_mov_b32_dpp v6, v6 quad_perm:[1,0,3,2] row_mask:0xf bank_mask:0xf bound_ctrl:1
	v_fmac_f32_e32 v6, v33, v33
	s_nop 1
	v_add_f32_dpp v6, v6, v6 quad_perm:[2,3,0,1] row_mask:0xf bank_mask:0xf bound_ctrl:1
	s_nop 1
	v_add_f32_dpp v6, v6, v6 row_half_mirror row_mask:0xf bank_mask:0xf bound_ctrl:1
	s_nop 1
	v_add_f32_dpp v6, v6, v6 row_mirror row_mask:0xf bank_mask:0xf bound_ctrl:1
	s_nop 0
	v_readlane_b32 s13, v6, 16
	v_readlane_b32 s14, v6, 48
	v_readlane_b32 s4, v6, 0
	v_readlane_b32 s5, v6, 32
	v_mov_b32_e32 v6, s13
	v_mov_b32_e32 v7, s14
	v_pk_add_f32 v[6:7], s[4:5], v[6:7]
	v_readlane_b32 s5, v8, 16
	v_readlane_b32 s4, v8, 0
	v_mov_b32_e32 v11, v6
	v_mov_b32_e32 v9, s5
	v_readlane_b32 s5, v8, 48
	v_add_f32_e32 v9, s4, v9
	v_readlane_b32 s4, v8, 32
	v_mov_b32_e32 v8, s5
	s_nop 0
	v_add_f32_e32 v8, s4, v8
	v_add_f32_e32 v12, v9, v8
	s_nop 0
	v_add_f32_dpp v8, v31, v31 quad_perm:[1,0,3,2] row_mask:0xf bank_mask:0xf bound_ctrl:1
	s_nop 1
	v_add_f32_dpp v8, v8, v8 quad_perm:[2,3,0,1] row_mask:0xf bank_mask:0xf bound_ctrl:1
	s_nop 1
	v_add_f32_dpp v8, v8, v8 row_half_mirror row_mask:0xf bank_mask:0xf bound_ctrl:1
	s_nop 1
	v_add_f32_dpp v8, v8, v8 row_mirror row_mask:0xf bank_mask:0xf bound_ctrl:1
	s_nop 0
	v_readlane_b32 s13, v8, 16
	v_readlane_b32 s14, v8, 48
	v_readlane_b32 s4, v8, 0
	v_readlane_b32 s5, v8, 32
	v_mov_b32_e32 v8, s13
	v_mov_b32_e32 v9, s14
	v_pk_add_f32 v[8:9], s[4:5], v[8:9]
	s_nop 0
	v_add_f32_e32 v8, v8, v9
	v_fmac_f32_e32 v31, 0xbc800000, v8
	v_mul_f32_e32 v8, v31, v31
	s_nop 1
	v_mov_b32_dpp v8, v8 quad_perm:[1,0,3,2] row_mask:0xf bank_mask:0xf bound_ctrl:1
	v_fmac_f32_e32 v8, v31, v31
	s_nop 1
	v_add_f32_dpp v8, v8, v8 quad_perm:[2,3,0,1] row_mask:0xf bank_mask:0xf bound_ctrl:1
	s_nop 1
	v_add_f32_dpp v8, v8, v8 row_half_mirror row_mask:0xf bank_mask:0xf bound_ctrl:1
	s_nop 1
	v_add_f32_dpp v8, v8, v8 row_mirror row_mask:0xf bank_mask:0xf bound_ctrl:1
	s_nop 0
	v_readlane_b32 s13, v8, 16
	v_readlane_b32 s14, v8, 48
	v_readlane_b32 s4, v8, 0
	v_readlane_b32 s5, v8, 32
	v_mov_b32_e32 v8, s13
	v_mov_b32_e32 v9, s14
	v_pk_add_f32 v[8:9], s[4:5], v[8:9]
	s_nop 0
	v_mov_b32_e32 v10, v8
	v_mov_b32_e32 v6, v9
	v_pk_add_f32 v[6:7], v[10:11], v[6:7]
	s_nop 0
	v_pk_fma_f32 v[6:7], v[6:7], s[46:47], v[14:15] op_sel_hi:[1,0,0]
	s_nop 0
	v_mul_f32_e32 v8, 0x4b800000, v7
	v_cmp_gt_f32_e64 s[4:5], s44, v7
	v_cmp_gt_f32_e32 vcc, s44, v6
	s_nop 0
	v_cndmask_b32_e64 v7, v7, v8, s[4:5]
	v_rsq_f32_e32 v7, v7
	s_nop 0
	v_mul_f32_e32 v8, 0x45800000, v7
	v_cndmask_b32_e64 v7, v7, v8, s[4:5]
	v_mul_f32_e32 v7, v33, v7
	v_fma_f32 v7, v35, v7, v34
	v_fmac_f32_e32 v7, v12, v32
	v_mul_f32_e32 v4, v4, v7
	v_cvt_pk_bf16_f32 v4, v4, s0
	ds_write_b16 v45, v4 offset:14336
	v_mul_f32_e32 v4, 0x4b800000, v6
	v_cndmask_b32_e32 v4, v6, v4, vcc
	v_rsq_f32_e32 v4, v4
	s_nop 0
	v_mul_f32_e32 v6, 0x45800000, v4
	v_cndmask_b32_e32 v4, v4, v6, vcc
	v_mul_f32_e32 v6, v30, v29
	v_mul_f32_e32 v7, v6, v36
	v_mul_f32_e32 v4, v31, v4
	v_fma_f32 v4, v35, v4, v34
	v_mov_b32_dpp v7, v7 quad_perm:[1,0,3,2] row_mask:0xf bank_mask:0xf bound_ctrl:1
	v_fmac_f32_e32 v7, v6, v36
	s_nop 1
	v_add_f32_dpp v6, v7, v7 quad_perm:[2,3,0,1] row_mask:0xf bank_mask:0xf bound_ctrl:1
	s_nop 1
	v_add_f32_dpp v6, v6, v6 row_half_mirror row_mask:0xf bank_mask:0xf bound_ctrl:1
	s_nop 1
	v_add_f32_dpp v6, v6, v6 row_mirror row_mask:0xf bank_mask:0xf bound_ctrl:1
	s_nop 0
	v_readlane_b32 s5, v6, 16
	v_readlane_b32 s4, v6, 0
	s_nop 0
	v_mov_b32_e32 v7, s5
	v_readlane_b32 s5, v6, 48
	v_add_f32_e32 v7, s4, v7
	v_readlane_b32 s4, v6, 32
	v_mov_b32_e32 v6, s5
	s_nop 0
	v_add_f32_e32 v6, s4, v6
	v_add_f32_e32 v6, v7, v6
	v_fmac_f32_e32 v4, v6, v28
	v_mul_f32_e32 v4, v5, v4
	v_cvt_pk_bf16_f32 v4, v4, s0
	ds_write_b16 v45, v4 offset:14848
	v_mul_f32_e32 v6, v27, v26
	v_add_f32_dpp v4, v25, v25 quad_perm:[1,0,3,2] row_mask:0xf bank_mask:0xf bound_ctrl:1
	v_mul_f32_e32 v7, v6, v36
	s_nop 0
	v_add_f32_dpp v4, v4, v4 quad_perm:[2,3,0,1] row_mask:0xf bank_mask:0xf bound_ctrl:1
	v_mov_b32_dpp v7, v7 quad_perm:[1,0,3,2] row_mask:0xf bank_mask:0xf bound_ctrl:1
	v_fmac_f32_e32 v7, v6, v36
	v_add_f32_dpp v4, v4, v4 row_half_mirror row_mask:0xf bank_mask:0xf bound_ctrl:1
	s_nop 0
	v_add_f32_dpp v6, v7, v7 quad_perm:[2,3,0,1] row_mask:0xf bank_mask:0xf bound_ctrl:1
	v_add_f32_dpp v4, v4, v4 row_mirror row_mask:0xf bank_mask:0xf bound_ctrl:1
	s_nop 0
	v_readlane_b32 s13, v4, 16
	v_readlane_b32 s14, v4, 48
	v_readlane_b32 s4, v4, 0
	v_readlane_b32 s5, v4, 32
	v_mov_b32_e32 v4, s13
	v_mov_b32_e32 v5, s14
	v_pk_add_f32 v[4:5], s[4:5], v[4:5]
	v_add_f32_dpp v6, v6, v6 row_half_mirror row_mask:0xf bank_mask:0xf bound_ctrl:1
	v_add_f32_e32 v4, v4, v5
	v_fmac_f32_e32 v25, 0xbc800000, v4
	v_mul_f32_e32 v4, v25, v25
	v_add_f32_dpp v6, v6, v6 row_mirror row_mask:0xf bank_mask:0xf bound_ctrl:1
	s_nop 0
	v_mov_b32_dpp v4, v4 quad_perm:[1,0,3,2] row_mask:0xf bank_mask:0xf bound_ctrl:1
	v_fmac_f32_e32 v4, v25, v25
	s_nop 1
	v_add_f32_dpp v4, v4, v4 quad_perm:[2,3,0,1] row_mask:0xf bank_mask:0xf bound_ctrl:1
	s_nop 1
	v_add_f32_dpp v4, v4, v4 row_half_mirror row_mask:0xf bank_mask:0xf bound_ctrl:1
	s_nop 1
	v_add_f32_dpp v4, v4, v4 row_mirror row_mask:0xf bank_mask:0xf bound_ctrl:1
	s_nop 0
	v_readlane_b32 s13, v4, 16
	v_readlane_b32 s14, v4, 48
	v_readlane_b32 s4, v4, 0
	v_readlane_b32 s5, v4, 32
	v_mov_b32_e32 v4, s13
	v_mov_b32_e32 v5, s14
	v_pk_add_f32 v[4:5], s[4:5], v[4:5]
	v_readlane_b32 s5, v6, 16
	v_readlane_b32 s4, v6, 0
	v_mov_b32_e32 v9, v4
	v_mov_b32_e32 v7, s5
	v_readlane_b32 s5, v6, 48
	v_add_f32_e32 v7, s4, v7
	v_readlane_b32 s4, v6, 32
	v_mov_b32_e32 v6, s5
	s_nop 0
	v_add_f32_e32 v6, s4, v6
	v_add_f32_e32 v10, v7, v6
	s_nop 0
	v_add_f32_dpp v6, v23, v23 quad_perm:[1,0,3,2] row_mask:0xf bank_mask:0xf bound_ctrl:1
	s_nop 1
	v_add_f32_dpp v6, v6, v6 quad_perm:[2,3,0,1] row_mask:0xf bank_mask:0xf bound_ctrl:1
	s_nop 1
	v_add_f32_dpp v6, v6, v6 row_half_mirror row_mask:0xf bank_mask:0xf bound_ctrl:1
	s_nop 1
	v_add_f32_dpp v6, v6, v6 row_mirror row_mask:0xf bank_mask:0xf bound_ctrl:1
	s_nop 0
	v_readlane_b32 s13, v6, 16
	v_readlane_b32 s14, v6, 48
	v_readlane_b32 s4, v6, 0
	v_readlane_b32 s5, v6, 32
	v_mov_b32_e32 v6, s13
	v_mov_b32_e32 v7, s14
	v_pk_add_f32 v[6:7], s[4:5], v[6:7]
	s_nop 0
	v_add_f32_e32 v6, v6, v7
	v_fmac_f32_e32 v23, 0xbc800000, v6
	v_mul_f32_e32 v6, v23, v23
	s_nop 1
	v_mov_b32_dpp v6, v6 quad_perm:[1,0,3,2] row_mask:0xf bank_mask:0xf bound_ctrl:1
	v_fmac_f32_e32 v6, v23, v23
	s_nop 1
	v_add_f32_dpp v6, v6, v6 quad_perm:[2,3,0,1] row_mask:0xf bank_mask:0xf bound_ctrl:1
	s_nop 1
	v_add_f32_dpp v6, v6, v6 row_half_mirror row_mask:0xf bank_mask:0xf bound_ctrl:1
	s_nop 1
	v_add_f32_dpp v6, v6, v6 row_mirror row_mask:0xf bank_mask:0xf bound_ctrl:1
	s_nop 0
	v_readlane_b32 s13, v6, 16
	v_readlane_b32 s14, v6, 48
	v_readlane_b32 s4, v6, 0
	v_readlane_b32 s5, v6, 32
	v_mov_b32_e32 v6, s13
	v_mov_b32_e32 v7, s14
	v_pk_add_f32 v[6:7], s[4:5], v[6:7]
	s_nop 0
	v_mov_b32_e32 v8, v6
	v_mov_b32_e32 v4, v7
	v_pk_add_f32 v[4:5], v[8:9], v[4:5]
	s_nop 0
	v_pk_fma_f32 v[4:5], v[4:5], s[46:47], v[14:15] op_sel_hi:[1,0,0]
	s_nop 0
	v_mul_f32_e32 v6, 0x4b800000, v5
	v_cmp_gt_f32_e64 s[4:5], s44, v5
	v_cmp_gt_f32_e32 vcc, s44, v4
	s_nop 0
	v_cndmask_b32_e64 v5, v5, v6, s[4:5]
	v_rsq_f32_e32 v5, v5
	s_nop 0
	v_mul_f32_e32 v6, 0x45800000, v5
	v_cndmask_b32_e64 v5, v5, v6, s[4:5]
	v_mul_f32_e32 v5, v25, v5
	v_fma_f32 v5, v35, v5, v34
	v_fmac_f32_e32 v5, v10, v24
	v_mul_f32_e32 v2, v2, v5
	v_cvt_pk_bf16_f32 v2, v2, s0
	ds_write_b16 v45, v2 offset:15360
	v_mul_f32_e32 v2, 0x4b800000, v4
	v_cndmask_b32_e32 v2, v4, v2, vcc
	v_rsq_f32_e32 v2, v2
	s_nop 0
	v_mul_f32_e32 v4, 0x45800000, v2
	v_cndmask_b32_e32 v2, v2, v4, vcc
	v_mul_f32_e32 v2, v23, v2
	v_fmac_f32_e32 v34, v35, v2
	v_mul_f32_e32 v2, v22, v21
	v_mul_f32_e32 v4, v2, v36
	s_nop 1
	v_mov_b32_dpp v4, v4 quad_perm:[1,0,3,2] row_mask:0xf bank_mask:0xf bound_ctrl:1
	v_fmac_f32_e32 v4, v2, v36
	s_nop 1
	v_add_f32_dpp v2, v4, v4 quad_perm:[2,3,0,1] row_mask:0xf bank_mask:0xf bound_ctrl:1
	s_nop 1
	v_add_f32_dpp v2, v2, v2 row_half_mirror row_mask:0xf bank_mask:0xf bound_ctrl:1
	s_nop 1
	v_add_f32_dpp v2, v2, v2 row_mirror row_mask:0xf bank_mask:0xf bound_ctrl:1
	s_nop 0
	v_readlane_b32 s5, v2, 16
	v_readlane_b32 s4, v2, 0
	s_nop 0
	v_mov_b32_e32 v4, s5
	v_readlane_b32 s5, v2, 48
	v_add_f32_e32 v4, s4, v4
	v_readlane_b32 s4, v2, 32
	v_mov_b32_e32 v2, s5
	s_nop 0
	v_add_f32_e32 v2, s4, v2
	v_add_f32_e32 v2, v4, v2
	v_fmac_f32_e32 v34, v2, v1
	v_mul_f32_e32 v1, v3, v34
	v_cvt_pk_bf16_f32 v1, v1, s0
	ds_write_b16 v45, v1 offset:15872
	v_lshlrev_b32_e32 v1, 4, v0
	v_and_b32_e32 v176, 0x1f0, v1
	v_add_u32_e32 v6, 16, v176
	v_ashrrev_i32_e32 v4, 5, v0
	v_lshl_add_u32 v0, v4, 9, v6
	s_waitcnt lgkmcnt(0)
	s_barrier
	ds_read_b128 v[0:3], v0 offset:8192
	v_add_u32_e32 v4, s12, v4
	v_ashrrev_i32_e32 v5, 31, v4
	v_lshlrev_b64 v[4:5], 9, v[4:5]
	v_lshl_add_u64 v[4:5], s[28:29], 0, v[4:5]
	v_lshl_add_u64 v[4:5], v[4:5], 0, v[176:177]
	s_waitcnt lgkmcnt(0)
	global_store_dwordx4 v[4:5], v[0:3], off
	v_ashrrev_i32_e32 v4, 5, v20
	s_nop 0
	v_lshl_add_u32 v0, v4, 9, v6
	ds_read_b128 v[0:3], v0 offset:8192
	v_add_u32_e32 v4, s12, v4
	v_ashrrev_i32_e32 v5, 31, v4
	v_lshlrev_b64 v[4:5], 9, v[4:5]
	v_lshl_add_u64 v[4:5], s[28:29], 0, v[4:5]
	v_lshl_add_u64 v[4:5], v[4:5], 0, v[176:177]
	s_waitcnt lgkmcnt(0)
	global_store_dwordx4 v[4:5], v[0:3], off
	s_barrier
	s_branch .LBB0_584
